# m3_attn_pipe_dmaspread
# speedup vs baseline: 1.0149x; 1.0149x over previous
; template <int MODE>
; __device__ __forceinline__ void attn_unit(LAS unsigned char* lds, const bf16_t* __restrict__ proj, bf16_t* __restrict__ mix, int b, int qblk, int hj,
;                                           const float* __restrict__ sink, const float* __restrict__ subln, float lam, float post) {
;     ...
;     f32x16 O[NEB];
; #pragma unroll
;     for (int e = 0; e < NEB; ++e)
; #pragma unroll
;         for (int r = 0; r < 16; ++r) O[e][r] = 0.f;
.LBB0_182:
	s_add_i32 s0, s97, 0xffffff40
	s_and_b32 s99, s0, 0xfc0
	s_mul_i32 s18, s99, 0x1200
	s_waitcnt vmcnt(4)
	s_barrier
	v_lshl_add_u64 v[248:249], v[160:161], 0, s[18:19]
	s_add_i32 s100, s85, 0xe000
	s_add_i32 s101, s85, 0x1e000
	v_lshl_add_u64 v[250:251], v[248:249], 0, s[22:23]
	s_add_i32 m0, s85, 0xc000
	s_nop 0
	global_load_lds_dwordx4 v[250:251], off
	ds_read_b128 v[146:149], v169 offset:8192
	ds_read_b128 v[150:153], v170 offset:8192
	ds_read_b128 v[182:185], v171 offset:8192
	ds_read_b128 v[198:201], v172 offset:8192
	ds_read_b64_tr_b16 v[118:119], v173
	ds_read_b64_tr_b16 v[120:121], v174
	ds_read_b64_tr_b16 v[124:125], v174 offset:4096
	ds_read_b64_tr_b16 v[122:123], v173 offset:4096
	ds_read_b64_tr_b16 v[134:135], v175
	ds_read_b64_tr_b16 v[136:137], v176
	ds_read_b64_tr_b16 v[132:133], v176 offset:4096
	ds_read_b64_tr_b16 v[130:131], v175 offset:4096
	ds_read_b64_tr_b16 v[138:139], v177
	ds_read_b64_tr_b16 v[140:141], v178
	ds_read_b64_tr_b16 v[128:129], v178 offset:4096
	ds_read_b64_tr_b16 v[126:127], v177 offset:4096
	ds_read_b64_tr_b16 v[142:143], v179
	ds_read_b64_tr_b16 v[144:145], v180
	ds_read_b64_tr_b16 v[116:117], v180 offset:4096
	ds_read_b64_tr_b16 v[114:115], v179 offset:4096
	s_waitcnt lgkmcnt(0)
	v_mfma_f32_32x32x16_bf16 v[82:97], v[146:149], v[98:101], v[82:97]
	s_and_b64 vcc, exec, s[44:45]
	s_mov_b64 s[42:43], s[44:45]
	v_mfma_f32_32x32x16_bf16 v[82:97], v[150:153], v[102:105], v[82:97]
	v_mfma_f32_32x32x16_bf16 v[82:97], v[182:185], v[106:109], v[82:97]
	v_mfma_f32_32x32x16_bf16 v[82:97], v[198:201], v[110:113], v[82:97]
	s_cbranch_vccnz .LBB0_184
	v_exp_f32_e32 v185, v66
	v_exp_f32_e32 v198, v67
	v_exp_f32_e32 v199, v68
	v_exp_f32_e32 v200, v69
	v_add_f32_e32 v201, 0, v185
	v_exp_f32_e32 v202, v70
	v_add_f32_e32 v201, v198, v201
	v_exp_f32_e32 v203, v71
	v_add_f32_e32 v201, v199, v201
	v_exp_f32_e32 v204, v72
	v_add_f32_e32 v201, v200, v201
	v_exp_f32_e32 v205, v73
	v_exp_f32_e32 v150, v74
	v_exp_f32_e32 v151, v75
	v_add_f32_e32 v201, v202, v201
	v_add_f32_e32 v201, v203, v201
	v_exp_f32_e32 v152, v76
	v_add_f32_e32 v201, v204, v201
	v_exp_f32_e32 v153, v77
	v_add_f32_e32 v201, v205, v201
	v_exp_f32_e32 v164, v78
	v_cvt_pk_bf16_f32 v146, v150, v151
	v_add_f32_e32 v150, v150, v201
	v_exp_f32_e32 v182, v79
	v_add_f32_e32 v150, v151, v150
	v_exp_f32_e32 v183, v80
	v_add_f32_e32 v150, v152, v150
	v_exp_f32_e32 v184, v81
	v_add_f32_e32 v150, v153, v150
	v_add_f32_e32 v150, v164, v150
	v_add_f32_e32 v150, v182, v150
	v_add_f32_e32 v150, v183, v150
	v_cvt_pk_bf16_f32 v148, v164, v182
	v_add_f32_e32 v247, v184, v150
	v_cmp_nge_f32_e32 vcc, s12, v247
	s_cmp_lg_u64 vcc, 0
	v_cvt_pk_bf16_f32 v147, v152, v153
	v_cvt_pk_bf16_f32 v149, v183, v184
	v_cvt_pk_bf16_f32 v150, v185, v198
	v_cvt_pk_bf16_f32 v151, v199, v200
	v_cvt_pk_bf16_f32 v152, v202, v203
	v_cvt_pk_bf16_f32 v153, v204, v205
	s_cselect_b64 s[42:43], -1, 0

.LBB0_186:
	v_mfma_f32_32x32x16_bf16 v[50:65], v[118:121], v[150:153], v[50:65]
	ds_read_b128 v[182:185], v169 offset:16384
	ds_read_b128 v[198:201], v170 offset:16384
	ds_read_b128 v[202:205], v171 offset:16384
	s_add_i32 s0, s97, 0xfffffec0
	s_and_b32 s0, s0, 0xfc0
	v_or_b32_e32 v66, s0, v166
	v_sub_u32_e32 v66, v167, v66
	v_cvt_f32_i32_e32 v67, v66
	s_cmp_lt_u32 s0, s84
	s_cselect_b64 s[42:43], -1, 0
	v_mfma_f32_32x32x16_bf16 v[34:49], v[134:137], v[150:153], v[34:49]
	ds_read_b128 v[206:209], v172 offset:16384
	ds_read_b64_tr_b16 v[118:119], v179 offset:8192
	ds_read_b64_tr_b16 v[120:121], v180 offset:8192
	v_fma_f32 v80, -v158, |v67|, -v0
	s_cmp_lg_u32 s0, s84
	v_mfma_f32_32x32x16_bf16 v[18:33], v[138:141], v[150:153], v[18:33]
	ds_read_b64_tr_b16 v[134:135], v175 offset:12288
	ds_read_b64_tr_b16 v[136:137], v176 offset:12288
	ds_read_b64_tr_b16 v[138:139], v177 offset:12288
	v_mfma_f32_32x32x16_bf16 v[2:17], v[142:145], v[150:153], v[2:17]
	ds_read_b64_tr_b16 v[140:141], v178 offset:12288
	ds_read_b64_tr_b16 v[142:143], v179 offset:12288
	ds_read_b64_tr_b16 v[144:145], v180 offset:12288
	v_lshl_add_u64 v[250:251], v[248:249], 0, s[56:57]
	s_mov_b32 m0, s100
	s_nop 0
	global_load_lds_dwordx4 v[250:251], off
	v_mfma_f32_32x32x16_bf16 v[50:65], v[122:125], v[146:149], v[50:65]
	ds_read_b64_tr_b16 v[122:123], v177 offset:8192
	ds_read_b64_tr_b16 v[124:125], v178 offset:8192
	v_mfma_f32_32x32x16_bf16 v[34:49], v[130:133], v[146:149], v[34:49]
	ds_read_b64_tr_b16 v[130:131], v173 offset:8192
	ds_read_b64_tr_b16 v[132:133], v174 offset:8192
	v_mfma_f32_32x32x16_bf16 v[18:33], v[126:129], v[146:149], v[18:33]
	ds_read_b64_tr_b16 v[126:127], v175 offset:8192
	ds_read_b64_tr_b16 v[128:129], v176 offset:8192
	v_mfma_f32_32x32x16_bf16 v[2:17], v[114:117], v[146:149], v[2:17]
	ds_read_b64_tr_b16 v[114:115], v173 offset:12288
	ds_read_b64_tr_b16 v[116:117], v174 offset:12288
	s_cbranch_scc1 .LBB0_188
	v_add_u32_e32 v67, -2, v66
	v_cvt_f32_i32_e32 v67, v67
	v_add_u32_e32 v68, -1, v66
	v_cvt_f32_i32_e32 v68, v68
	v_add_u32_e32 v70, -8, v66
	v_and_b32_e32 v69, 0x7fffffff, v67
	v_add_u32_e32 v67, -3, v66
	v_cvt_f32_i32_e32 v67, v67
	v_cvt_f32_i32_e32 v70, v70
	v_and_b32_e32 v68, 0x7fffffff, v68
	v_pk_fma_f32 v[210:211], v[162:163], v[68:69], v[0:1] op_sel_hi:[1,1,0] neg_lo:[0,0,1] neg_hi:[0,0,1]
	v_and_b32_e32 v68, 0x7fffffff, v67
	v_add_u32_e32 v67, -10, v66
	v_cvt_f32_i32_e32 v67, v67
	v_and_b32_e32 v69, 0x7fffffff, v70
	v_pk_fma_f32 v[212:213], v[162:163], v[68:69], v[0:1] op_sel_hi:[1,1,0] neg_lo:[0,0,1] neg_hi:[0,0,1]
	v_add_u32_e32 v68, -9, v66
	v_cvt_f32_i32_e32 v68, v68
	v_and_b32_e32 v69, 0x7fffffff, v67
	v_add_u32_e32 v67, -16, v66
	v_cvt_f32_i32_e32 v67, v67
	v_add_u32_e32 v70, -11, v66
	v_cvt_f32_i32_e32 v70, v70
	v_and_b32_e32 v68, 0x7fffffff, v68
	v_pk_fma_f32 v[214:215], v[162:163], v[68:69], v[0:1] op_sel_hi:[1,1,0] neg_lo:[0,0,1] neg_hi:[0,0,1]
	v_and_b32_e32 v69, 0x7fffffff, v67
	v_subrev_u32_e32 v67, 18, v66
	v_cvt_f32_i32_e32 v67, v67
	v_and_b32_e32 v68, 0x7fffffff, v70
	v_pk_fma_f32 v[216:217], v[162:163], v[68:69], v[0:1] op_sel_hi:[1,1,0] neg_lo:[0,0,1] neg_hi:[0,0,1]
	v_subrev_u32_e32 v68, 17, v66
	v_cvt_f32_i32_e32 v68, v68
	v_and_b32_e32 v69, 0x7fffffff, v67
	v_subrev_u32_e32 v67, 24, v66
	v_subrev_u32_e32 v70, 19, v66
	v_cvt_f32_i32_e32 v67, v67
	v_cvt_f32_i32_e32 v70, v70
	v_and_b32_e32 v68, 0x7fffffff, v68
	v_pk_fma_f32 v[218:219], v[162:163], v[68:69], v[0:1] op_sel_hi:[1,1,0] neg_lo:[0,0,1] neg_hi:[0,0,1]
	v_and_b32_e32 v69, 0x7fffffff, v67
	v_and_b32_e32 v68, 0x7fffffff, v70
	v_pk_fma_f32 v[220:221], v[162:163], v[68:69], v[0:1] op_sel_hi:[1,1,0] neg_lo:[0,0,1] neg_hi:[0,0,1]
	v_subrev_u32_e32 v67, 26, v66
	v_subrev_u32_e32 v68, 25, v66
	v_cvt_f32_i32_e32 v67, v67
	v_cvt_f32_i32_e32 v68, v68
	v_subrev_u32_e32 v66, 27, v66
	v_cvt_f32_i32_e32 v69, v66
	v_and_b32_e32 v67, 0x7fffffff, v67
	v_and_b32_e32 v66, 0x7fffffff, v68
	v_mov_b32_e32 v81, v210
	v_pk_fma_f32 v[222:223], v[162:163], v[66:67], v[0:1] op_sel_hi:[1,1,0] neg_lo:[0,0,1] neg_hi:[0,0,1]
	v_fma_f32 v224, -v158, |v69|, -v0
	v_mov_b64_e32 v[66:67], v[80:81]
	v_mov_b64_e32 v[68:69], v[82:83]
	v_mov_b64_e32 v[70:71], v[84:85]
	v_mov_b64_e32 v[72:73], v[86:87]
	v_mov_b64_e32 v[74:75], v[88:89]
	v_mov_b64_e32 v[76:77], v[90:91]
	v_mov_b64_e32 v[78:79], v[92:93]
	v_mov_b64_e32 v[80:81], v[94:95]
	v_mov_b32_e32 v68, v211
	v_mov_b32_e32 v69, v212
	v_mov_b32_e32 v70, v213
	v_mov_b32_e32 v71, v214
	v_mov_b32_e32 v72, v215
	v_mov_b32_e32 v73, v216
	v_mov_b32_e32 v74, v217
	v_mov_b32_e32 v75, v218
	v_mov_b32_e32 v76, v219
	v_mov_b32_e32 v77, v220
	v_mov_b32_e32 v78, v221
	v_mov_b32_e32 v79, v222
	v_mov_b32_e32 v80, v223
	v_mov_b32_e32 v81, v224
	s_branch .LBB0_189

.LBB0_189:
	v_lshl_add_u64 v[250:251], v[248:249], 0, s[68:69]
	s_add_i32 m0, s85, 0x1c000
	s_nop 0
	global_load_lds_dwordx4 v[250:251], off
	v_add_f32_e32 v147, v247, v181
	s_waitcnt lgkmcnt(0)
	v_mfma_f32_32x32x16_bf16 v[66:81], v[182:185], v[98:101], v[66:81]
	v_exp_f32_e32 v149, v82
	v_exp_f32_e32 v150, v83
	v_exp_f32_e32 v151, v84
	v_exp_f32_e32 v152, v85
	v_add_f32_e32 v146, 0, v149
	v_exp_f32_e32 v153, v86
	v_add_f32_e32 v146, v150, v146
	v_mfma_f32_32x32x16_bf16 v[66:81], v[198:201], v[102:105], v[66:81]
	v_exp_f32_e32 v164, v87
	v_add_f32_e32 v146, v151, v146
	v_exp_f32_e32 v181, v88
	v_add_f32_e32 v146, v152, v146
	v_exp_f32_e32 v182, v89
	v_add_f32_e32 v146, v153, v146
	v_exp_f32_e32 v183, v90
	v_mfma_f32_32x32x16_bf16 v[66:81], v[202:205], v[106:109], v[66:81]
	v_add_f32_e32 v146, v164, v146
	v_exp_f32_e32 v184, v91
	v_add_f32_e32 v146, v181, v146
	v_exp_f32_e32 v185, v92
	v_add_f32_e32 v146, v182, v146
	v_exp_f32_e32 v198, v93
	v_add_f32_e32 v146, v183, v146
	v_exp_f32_e32 v199, v94
	v_add_f32_e32 v146, v184, v146
	v_exp_f32_e32 v200, v95
	v_mfma_f32_32x32x16_bf16 v[66:81], v[206:209], v[110:113], v[66:81]
	v_add_f32_e32 v146, v185, v146
	v_exp_f32_e32 v201, v96
	v_add_f32_e32 v146, v198, v146
	v_exp_f32_e32 v202, v97
	v_add_f32_e32 v146, v199, v146
	v_add_f32_e32 v146, v200, v146
	v_add_f32_e32 v146, v201, v146
	v_add_f32_e32 v148, v202, v146
	v_cmp_nge_f32_e32 vcc, s12, v148
	s_cbranch_vccz .LBB0_191
	v_max_f32_e32 v146, v83, v83
	v_max_f32_e32 v148, v82, v82
	v_max_f32_e32 v146, v148, v146
	v_max3_f32 v146, v146, v84, v85
	v_max3_f32 v146, v146, v86, v87
	v_max3_f32 v146, v146, v88, v89
	v_max3_f32 v146, v146, v90, v91
	v_max3_f32 v146, v146, v92, v93
	v_max3_f32 v146, v146, v94, v95
	v_max3_f32 v146, v146, v96, v97
	ds_bpermute_b32 v148, v159, v146
	s_waitcnt lgkmcnt(0)
	v_max3_f32 v148, v146, v148, 0
	v_sub_f32_e32 v82, v82, v148
	v_exp_f32_e32 v82, v82
	v_sub_f32_e32 v83, v83, v148
	v_exp_f32_e32 v83, v83
	v_sub_f32_e32 v84, v84, v148
	v_exp_f32_e32 v84, v84
	v_sub_f32_e32 v85, v85, v148
	v_exp_f32_e32 v85, v85
	v_sub_f32_e32 v86, v86, v148
	v_sub_f32_e32 v87, v87, v148
	v_add_f32_e32 v149, 0, v82
	v_exp_f32_e32 v86, v86
	v_exp_f32_e32 v87, v87
	v_add_f32_e32 v149, v83, v149
	v_sub_f32_e32 v88, v88, v148
	v_sub_f32_e32 v89, v89, v148
	v_add_f32_e32 v149, v84, v149
	v_exp_f32_e32 v88, v88
	v_exp_f32_e32 v89, v89
	v_add_f32_e32 v149, v85, v149
	v_add_f32_e32 v149, v86, v149
	v_cvt_pk_bf16_f32 v82, v82, v83
	v_cvt_pk_bf16_f32 v83, v84, v85
	v_cvt_pk_bf16_f32 v84, v86, v87
	v_sub_f32_e32 v86, v90, v148
	v_add_f32_e32 v149, v87, v149
	v_exp_f32_e32 v86, v86
	v_sub_f32_e32 v87, v91, v148
	v_add_f32_e32 v149, v88, v149
	v_cvt_pk_bf16_f32 v85, v88, v89
	v_exp_f32_e32 v87, v87
	v_sub_f32_e32 v88, v92, v148
	v_add_f32_e32 v149, v89, v149
	v_exp_f32_e32 v88, v88
	v_sub_f32_e32 v89, v93, v148
	v_exp_f32_e32 v89, v89
	v_sub_f32_e32 v91, v94, v148
	v_add_f32_e32 v90, v86, v149
	v_exp_f32_e32 v91, v91
	v_sub_f32_e32 v92, v95, v148
	v_add_f32_e32 v90, v87, v90
	v_exp_f32_e32 v92, v92
	v_sub_f32_e32 v93, v96, v148
	v_add_f32_e32 v90, v88, v90
	v_exp_f32_e32 v93, v93
	v_sub_f32_e32 v94, v97, v148
	v_exp_f32_e64 v146, -v148
	v_add_f32_e32 v90, v89, v90
	v_exp_f32_e32 v94, v94
	v_add_f32_e32 v90, v91, v90
	v_add_f32_e32 v90, v92, v90
	v_add_f32_e32 v0, v0, v148
	v_add_f32_e32 v90, v93, v90
	v_pk_mul_f32 v[64:65], v[64:65], v[146:147] op_sel_hi:[1,0]
	v_pk_mul_f32 v[62:63], v[62:63], v[146:147] op_sel_hi:[1,0]
	v_pk_mul_f32 v[60:61], v[60:61], v[146:147] op_sel_hi:[1,0]
	v_pk_mul_f32 v[58:59], v[58:59], v[146:147] op_sel_hi:[1,0]
	v_pk_mul_f32 v[56:57], v[56:57], v[146:147] op_sel_hi:[1,0]
	v_pk_mul_f32 v[54:55], v[54:55], v[146:147] op_sel_hi:[1,0]
	v_pk_mul_f32 v[52:53], v[52:53], v[146:147] op_sel_hi:[1,0]
	v_pk_mul_f32 v[50:51], v[50:51], v[146:147] op_sel_hi:[1,0]
	v_pk_mul_f32 v[48:49], v[48:49], v[146:147] op_sel_hi:[1,0]
	v_pk_mul_f32 v[46:47], v[46:47], v[146:147] op_sel_hi:[1,0]
	v_pk_mul_f32 v[44:45], v[44:45], v[146:147] op_sel_hi:[1,0]
	v_pk_mul_f32 v[42:43], v[42:43], v[146:147] op_sel_hi:[1,0]
	v_pk_mul_f32 v[40:41], v[40:41], v[146:147] op_sel_hi:[1,0]
	v_pk_mul_f32 v[38:39], v[38:39], v[146:147] op_sel_hi:[1,0]
	v_pk_mul_f32 v[36:37], v[36:37], v[146:147] op_sel_hi:[1,0]
	v_pk_mul_f32 v[34:35], v[34:35], v[146:147] op_sel_hi:[1,0]
	v_pk_mul_f32 v[32:33], v[32:33], v[146:147] op_sel_hi:[1,0]
	v_pk_mul_f32 v[30:31], v[30:31], v[146:147] op_sel_hi:[1,0]
	v_pk_mul_f32 v[28:29], v[28:29], v[146:147] op_sel_hi:[1,0]
	v_pk_mul_f32 v[26:27], v[26:27], v[146:147] op_sel_hi:[1,0]
	v_pk_mul_f32 v[24:25], v[24:25], v[146:147] op_sel_hi:[1,0]
	v_pk_mul_f32 v[22:23], v[22:23], v[146:147] op_sel_hi:[1,0]
	v_pk_mul_f32 v[20:21], v[20:21], v[146:147] op_sel_hi:[1,0]
	v_pk_mul_f32 v[18:19], v[18:19], v[146:147] op_sel_hi:[1,0]
	v_pk_mul_f32 v[16:17], v[16:17], v[146:147] op_sel_hi:[1,0]
	v_pk_mul_f32 v[14:15], v[14:15], v[146:147] op_sel_hi:[1,0]
	v_pk_mul_f32 v[12:13], v[12:13], v[146:147] op_sel_hi:[1,0]
	v_pk_mul_f32 v[10:11], v[10:11], v[146:147] op_sel_hi:[1,0]
	v_pk_mul_f32 v[8:9], v[8:9], v[146:147] op_sel_hi:[1,0]
	v_pk_mul_f32 v[6:7], v[6:7], v[146:147] op_sel_hi:[1,0]
	v_pk_mul_f32 v[4:5], v[4:5], v[146:147] op_sel_hi:[1,0]
	v_pk_mul_f32 v[2:3], v[2:3], v[146:147] op_sel_hi:[1,0]
	v_sub_f32_e32 v81, v81, v148
	v_sub_f32_e32 v80, v80, v148
	v_sub_f32_e32 v79, v79, v148
	v_sub_f32_e32 v78, v78, v148
	v_sub_f32_e32 v77, v77, v148
	v_sub_f32_e32 v76, v76, v148
	v_sub_f32_e32 v75, v75, v148
	v_sub_f32_e32 v74, v74, v148
	v_sub_f32_e32 v73, v73, v148
	v_sub_f32_e32 v72, v72, v148
	v_sub_f32_e32 v71, v71, v148
	v_sub_f32_e32 v70, v70, v148
	v_sub_f32_e32 v69, v69, v148
	v_sub_f32_e32 v68, v68, v148
	v_sub_f32_e32 v67, v67, v148
	v_sub_f32_e32 v66, v66, v148
	v_add_f32_e32 v148, v94, v90
	v_cvt_pk_bf16_f32 v86, v86, v87
	v_cvt_pk_bf16_f32 v87, v88, v89
	v_cvt_pk_bf16_f32 v88, v91, v92
	v_cvt_pk_bf16_f32 v89, v93, v94
	v_mul_f32_e32 v147, v147, v146
	v_xor_b32_e32 v146, 0x80000000, v0
	s_branch .LBB0_192

.LBB0_192:
	v_mfma_f32_32x32x16_bf16 v[50:65], v[130:133], v[82:85], v[50:65]
	ds_read_b128 v[182:185], v169 offset:24576
	ds_read_b128 v[198:201], v170 offset:24576
	ds_read_b128 v[202:205], v171 offset:24576
	v_exp_f32_e32 v149, v66
	v_exp_f32_e32 v150, v67
	s_or_b32 s0, s0, 32
	s_cmp_lt_u32 s0, s84
	s_cselect_b64 s[42:43], -1, 0
	s_cmp_lg_u32 s0, s84
	v_mfma_f32_32x32x16_bf16 v[34:49], v[126:129], v[82:85], v[34:49]
	ds_read_b128 v[206:209], v172 offset:24576
	ds_read_b64_tr_b16 v[130:131], v173 offset:16384
	ds_read_b64_tr_b16 v[132:133], v174 offset:16384
	v_exp_f32_e32 v151, v68
	v_exp_f32_e32 v152, v69
	v_mfma_f32_32x32x16_bf16 v[18:33], v[122:125], v[82:85], v[18:33]
	ds_read_b64_tr_b16 v[126:127], v175 offset:16384
	ds_read_b64_tr_b16 v[128:129], v176 offset:16384
	ds_read_b64_tr_b16 v[122:123], v177 offset:16384
	v_exp_f32_e32 v153, v70
	v_exp_f32_e32 v164, v71
	v_mfma_f32_32x32x16_bf16 v[2:17], v[118:121], v[82:85], v[2:17]
	ds_read_b64_tr_b16 v[124:125], v178 offset:16384
	ds_read_b64_tr_b16 v[118:119], v179 offset:16384
	ds_read_b64_tr_b16 v[120:121], v180 offset:16384
	v_exp_f32_e32 v181, v72
	v_exp_f32_e32 v225, v73
	v_lshl_add_u64 v[250:251], v[248:249], 0, s[46:47]
	s_mov_b32 m0, s101
	s_nop 0
	global_load_lds_dwordx4 v[250:251], off
	v_or_b32_e32 v82, s0, v166
	v_sub_u32_e32 v82, v167, v82
	v_cvt_f32_i32_e32 v83, v82
	v_fma_f32 v96, -v158, |v83|, v146
	v_mfma_f32_32x32x16_bf16 v[50:65], v[114:117], v[86:89], v[50:65]
	ds_read_b64_tr_b16 v[114:115], v173 offset:20480
	ds_read_b64_tr_b16 v[116:117], v174 offset:20480
	v_exp_f32_e32 v226, v74
	v_exp_f32_e32 v227, v75
	v_mfma_f32_32x32x16_bf16 v[34:49], v[134:137], v[86:89], v[34:49]
	ds_read_b64_tr_b16 v[134:135], v175 offset:20480
	ds_read_b64_tr_b16 v[136:137], v176 offset:20480
	v_exp_f32_e32 v239, v76
	v_exp_f32_e32 v240, v77
	v_mfma_f32_32x32x16_bf16 v[18:33], v[138:141], v[86:89], v[18:33]
	ds_read_b64_tr_b16 v[138:139], v177 offset:20480
	ds_read_b64_tr_b16 v[140:141], v178 offset:20480
	v_exp_f32_e32 v241, v78
	v_exp_f32_e32 v242, v79
	v_mfma_f32_32x32x16_bf16 v[2:17], v[142:145], v[86:89], v[2:17]
	ds_read_b64_tr_b16 v[142:143], v179 offset:20480
	ds_read_b64_tr_b16 v[144:145], v180 offset:20480
	v_exp_f32_e32 v243, v80
	v_exp_f32_e32 v246, v81
	s_cbranch_scc1 .LBB0_194
	v_add_u32_e32 v83, -2, v82
	v_cvt_f32_i32_e32 v83, v83
	v_add_u32_e32 v84, -1, v82
	v_cvt_f32_i32_e32 v84, v84
	v_add_u32_e32 v86, -8, v82
	v_and_b32_e32 v85, 0x7fffffff, v83
	v_add_u32_e32 v83, -3, v82
	v_cvt_f32_i32_e32 v83, v83
	v_cvt_f32_i32_e32 v86, v86
	v_and_b32_e32 v84, 0x7fffffff, v84
	v_pk_fma_f32 v[210:211], v[162:163], v[84:85], v[146:147] op_sel_hi:[1,1,0]
	v_and_b32_e32 v84, 0x7fffffff, v83
	v_add_u32_e32 v83, -10, v82
	v_cvt_f32_i32_e32 v83, v83
	v_and_b32_e32 v85, 0x7fffffff, v86
	v_pk_fma_f32 v[212:213], v[162:163], v[84:85], v[146:147] op_sel_hi:[1,1,0]
	v_add_u32_e32 v84, -9, v82
	v_cvt_f32_i32_e32 v84, v84
	v_and_b32_e32 v85, 0x7fffffff, v83
	v_add_u32_e32 v83, -16, v82
	v_cvt_f32_i32_e32 v83, v83
	v_add_u32_e32 v86, -11, v82
	v_cvt_f32_i32_e32 v86, v86
	v_and_b32_e32 v84, 0x7fffffff, v84
	v_pk_fma_f32 v[214:215], v[162:163], v[84:85], v[146:147] op_sel_hi:[1,1,0]
	v_and_b32_e32 v85, 0x7fffffff, v83
	v_subrev_u32_e32 v83, 18, v82
	v_cvt_f32_i32_e32 v83, v83
	v_and_b32_e32 v84, 0x7fffffff, v86
	v_pk_fma_f32 v[216:217], v[162:163], v[84:85], v[146:147] op_sel_hi:[1,1,0]
	v_subrev_u32_e32 v84, 17, v82
	v_cvt_f32_i32_e32 v84, v84
	v_and_b32_e32 v85, 0x7fffffff, v83
	v_subrev_u32_e32 v83, 24, v82
	v_subrev_u32_e32 v86, 19, v82
	v_cvt_f32_i32_e32 v83, v83
	v_cvt_f32_i32_e32 v86, v86
	v_and_b32_e32 v84, 0x7fffffff, v84
	v_pk_fma_f32 v[218:219], v[162:163], v[84:85], v[146:147] op_sel_hi:[1,1,0]
	v_and_b32_e32 v85, 0x7fffffff, v83
	v_and_b32_e32 v84, 0x7fffffff, v86
	v_pk_fma_f32 v[220:221], v[162:163], v[84:85], v[146:147] op_sel_hi:[1,1,0]
	v_subrev_u32_e32 v83, 26, v82
	v_subrev_u32_e32 v84, 25, v82
	v_cvt_f32_i32_e32 v83, v83
	v_cvt_f32_i32_e32 v84, v84
	v_subrev_u32_e32 v82, 27, v82
	v_cvt_f32_i32_e32 v85, v82
	v_and_b32_e32 v83, 0x7fffffff, v83
	v_and_b32_e32 v82, 0x7fffffff, v84
	v_mov_b32_e32 v97, v210
	v_pk_fma_f32 v[222:223], v[162:163], v[82:83], v[146:147] op_sel_hi:[1,1,0]
	v_fma_f32 v224, -v158, |v85|, v146
	v_mov_b64_e32 v[82:83], v[96:97]
	v_mov_b64_e32 v[84:85], v[98:99]
	v_mov_b64_e32 v[86:87], v[100:101]
	v_mov_b64_e32 v[88:89], v[102:103]
	v_mov_b64_e32 v[90:91], v[104:105]
	v_mov_b64_e32 v[92:93], v[106:107]
	v_mov_b64_e32 v[94:95], v[108:109]
	v_mov_b64_e32 v[96:97], v[110:111]
	v_mov_b32_e32 v84, v211
	v_mov_b32_e32 v85, v212
	v_mov_b32_e32 v86, v213
	v_mov_b32_e32 v87, v214
	v_mov_b32_e32 v88, v215
	v_mov_b32_e32 v89, v216
	v_mov_b32_e32 v90, v217
	v_mov_b32_e32 v91, v218
	v_mov_b32_e32 v92, v219
	v_mov_b32_e32 v93, v220
	v_mov_b32_e32 v94, v221
	v_mov_b32_e32 v95, v222
	v_mov_b32_e32 v96, v223
	v_mov_b32_e32 v97, v224
	s_branch .LBB0_195
.LBB0_194:
	v_cndmask_b32_e64 v244, -v158, v158, s[42:43]
	v_fma_f32 v82, 0, v244, v96
	v_add_f32_e32 v83, v244, v96
	v_pk_fma_f32 v[84:85], v[244:245], s[26:27], v[96:97] op_sel_hi:[0,1,0]
	v_pk_fma_f32 v[86:87], v[244:245], s[28:29], v[96:97] op_sel_hi:[0,1,0]
	v_pk_fma_f32 v[88:89], v[244:245], s[30:31], v[96:97] op_sel_hi:[0,1,0]
	v_pk_fma_f32 v[90:91], v[244:245], s[34:35], v[96:97] op_sel_hi:[0,1,0]
	v_pk_fma_f32 v[92:93], v[244:245], s[36:37], v[96:97] op_sel_hi:[0,1,0]
	v_pk_fma_f32 v[94:95], v[244:245], s[14:15], v[96:97] op_sel_hi:[0,1,0]
	v_pk_fma_f32 v[96:97], v[244:245], s[10:11], v[96:97] op_sel_hi:[0,1,0]
.LBB0_195:
	s_waitcnt vmcnt(4)
	s_barrier
	s_cmp_gt_u32 s98, 59
	s_cselect_b64 s[42:43], -1, 0
	s_add_i32 s0, s97, 0xffffff80
	s_and_b32 s0, s0, 0xf80
	s_mul_i32 s18, s0, 0x1200
	v_lshl_add_u64 v[248:249], v[160:161], 0, s[18:19]
	v_lshl_add_u64 v[250:251], v[248:249], 0, s[22:23]
	s_mov_b32 m0, s85
	s_nop 0
	global_load_lds_dwordx4 v[250:251], off
.LBB0_197:
	v_add_f32_e32 v147, v148, v147
	s_waitcnt lgkmcnt(0)
	v_mfma_f32_32x32x16_bf16 v[82:97], v[182:185], v[98:101], v[82:97]
	v_add_f32_e32 v148, 0, v149
	v_add_f32_e32 v148, v150, v148
	v_mfma_f32_32x32x16_bf16 v[82:97], v[198:201], v[102:105], v[82:97]
	v_add_f32_e32 v148, v151, v148
	v_add_f32_e32 v148, v152, v148
	v_add_f32_e32 v148, v153, v148
	v_mfma_f32_32x32x16_bf16 v[82:97], v[202:205], v[106:109], v[82:97]
	v_add_f32_e32 v148, v164, v148
	v_add_f32_e32 v148, v181, v148
	v_add_f32_e32 v148, v225, v148
	v_add_f32_e32 v148, v226, v148
	v_add_f32_e32 v148, v227, v148
	v_mfma_f32_32x32x16_bf16 v[82:97], v[206:209], v[110:113], v[82:97]
	v_add_f32_e32 v148, v239, v148
	v_add_f32_e32 v148, v240, v148
	v_add_f32_e32 v148, v241, v148
	v_add_f32_e32 v148, v242, v148
	v_add_f32_e32 v148, v243, v148
	v_add_f32_e32 v148, v246, v148
	v_cmp_nge_f32_e32 vcc, s12, v148
	s_cbranch_vccz .LBB0_199
	v_max_f32_e32 v146, v67, v67
	v_max_f32_e32 v148, v66, v66
	v_max_f32_e32 v146, v148, v146
	v_max3_f32 v146, v146, v68, v69
	v_max3_f32 v146, v146, v70, v71
	v_max3_f32 v146, v146, v72, v73
	v_max3_f32 v146, v146, v74, v75
	v_max3_f32 v146, v146, v76, v77
	v_max3_f32 v146, v146, v78, v79
	v_max3_f32 v146, v146, v80, v81
	ds_bpermute_b32 v148, v159, v146
	s_waitcnt lgkmcnt(0)
	v_max3_f32 v148, v146, v148, 0
	v_sub_f32_e32 v66, v66, v148
	v_exp_f32_e32 v66, v66
	v_sub_f32_e32 v67, v67, v148
	v_exp_f32_e32 v67, v67
	v_sub_f32_e32 v68, v68, v148
	v_exp_f32_e32 v68, v68
	v_sub_f32_e32 v69, v69, v148
	v_exp_f32_e32 v69, v69
	v_sub_f32_e32 v70, v70, v148
	v_sub_f32_e32 v71, v71, v148
	v_add_f32_e32 v149, 0, v66
	v_exp_f32_e32 v70, v70
	v_exp_f32_e32 v71, v71
	v_add_f32_e32 v149, v67, v149
	v_sub_f32_e32 v72, v72, v148
	v_sub_f32_e32 v73, v73, v148
	v_add_f32_e32 v149, v68, v149
	v_exp_f32_e32 v72, v72
	v_exp_f32_e32 v73, v73
	v_add_f32_e32 v149, v69, v149
	v_add_f32_e32 v149, v70, v149
	v_cvt_pk_bf16_f32 v66, v66, v67
	v_cvt_pk_bf16_f32 v67, v68, v69
	v_cvt_pk_bf16_f32 v68, v70, v71
	v_sub_f32_e32 v70, v74, v148
	v_add_f32_e32 v149, v71, v149
	v_exp_f32_e32 v70, v70
	v_sub_f32_e32 v71, v75, v148
	v_add_f32_e32 v149, v72, v149
	v_cvt_pk_bf16_f32 v69, v72, v73
	v_exp_f32_e32 v71, v71
	v_sub_f32_e32 v72, v76, v148
	v_add_f32_e32 v149, v73, v149
	v_exp_f32_e32 v72, v72
	v_sub_f32_e32 v73, v77, v148
	v_exp_f32_e32 v73, v73
	v_sub_f32_e32 v75, v78, v148
	v_add_f32_e32 v74, v70, v149
	v_exp_f32_e32 v75, v75
	v_sub_f32_e32 v76, v79, v148
	v_add_f32_e32 v74, v71, v74
	v_exp_f32_e32 v76, v76
	v_sub_f32_e32 v77, v80, v148
	v_add_f32_e32 v74, v72, v74
	v_exp_f32_e32 v77, v77
	v_sub_f32_e32 v78, v81, v148
	v_exp_f32_e64 v146, -v148
	v_add_f32_e32 v74, v73, v74
	v_exp_f32_e32 v78, v78
	v_add_f32_e32 v74, v75, v74
	v_add_f32_e32 v74, v76, v74
	v_add_f32_e32 v0, v0, v148
	v_add_f32_e32 v74, v77, v74
	v_pk_mul_f32 v[64:65], v[64:65], v[146:147] op_sel_hi:[1,0]
	v_pk_mul_f32 v[62:63], v[62:63], v[146:147] op_sel_hi:[1,0]
	v_pk_mul_f32 v[60:61], v[60:61], v[146:147] op_sel_hi:[1,0]
	v_pk_mul_f32 v[58:59], v[58:59], v[146:147] op_sel_hi:[1,0]
	v_pk_mul_f32 v[56:57], v[56:57], v[146:147] op_sel_hi:[1,0]
	v_pk_mul_f32 v[54:55], v[54:55], v[146:147] op_sel_hi:[1,0]
	v_pk_mul_f32 v[52:53], v[52:53], v[146:147] op_sel_hi:[1,0]
	v_pk_mul_f32 v[50:51], v[50:51], v[146:147] op_sel_hi:[1,0]
	v_pk_mul_f32 v[48:49], v[48:49], v[146:147] op_sel_hi:[1,0]
	v_pk_mul_f32 v[46:47], v[46:47], v[146:147] op_sel_hi:[1,0]
	v_pk_mul_f32 v[44:45], v[44:45], v[146:147] op_sel_hi:[1,0]
	v_pk_mul_f32 v[42:43], v[42:43], v[146:147] op_sel_hi:[1,0]
	v_pk_mul_f32 v[40:41], v[40:41], v[146:147] op_sel_hi:[1,0]
	v_pk_mul_f32 v[38:39], v[38:39], v[146:147] op_sel_hi:[1,0]
	v_pk_mul_f32 v[36:37], v[36:37], v[146:147] op_sel_hi:[1,0]
	v_pk_mul_f32 v[34:35], v[34:35], v[146:147] op_sel_hi:[1,0]
	v_pk_mul_f32 v[32:33], v[32:33], v[146:147] op_sel_hi:[1,0]
	v_pk_mul_f32 v[30:31], v[30:31], v[146:147] op_sel_hi:[1,0]
	v_pk_mul_f32 v[28:29], v[28:29], v[146:147] op_sel_hi:[1,0]
	v_pk_mul_f32 v[26:27], v[26:27], v[146:147] op_sel_hi:[1,0]
	v_pk_mul_f32 v[24:25], v[24:25], v[146:147] op_sel_hi:[1,0]
	v_pk_mul_f32 v[22:23], v[22:23], v[146:147] op_sel_hi:[1,0]
	v_pk_mul_f32 v[20:21], v[20:21], v[146:147] op_sel_hi:[1,0]
	v_pk_mul_f32 v[18:19], v[18:19], v[146:147] op_sel_hi:[1,0]
	v_pk_mul_f32 v[16:17], v[16:17], v[146:147] op_sel_hi:[1,0]
	v_pk_mul_f32 v[14:15], v[14:15], v[146:147] op_sel_hi:[1,0]
	v_pk_mul_f32 v[12:13], v[12:13], v[146:147] op_sel_hi:[1,0]
	v_pk_mul_f32 v[10:11], v[10:11], v[146:147] op_sel_hi:[1,0]
	v_pk_mul_f32 v[8:9], v[8:9], v[146:147] op_sel_hi:[1,0]
	v_pk_mul_f32 v[6:7], v[6:7], v[146:147] op_sel_hi:[1,0]
	v_pk_mul_f32 v[4:5], v[4:5], v[146:147] op_sel_hi:[1,0]
	v_pk_mul_f32 v[2:3], v[2:3], v[146:147] op_sel_hi:[1,0]
	v_sub_f32_e32 v97, v97, v148
	v_sub_f32_e32 v96, v96, v148
	v_sub_f32_e32 v95, v95, v148
	v_sub_f32_e32 v94, v94, v148
	v_sub_f32_e32 v93, v93, v148
	v_sub_f32_e32 v92, v92, v148
	v_sub_f32_e32 v91, v91, v148
	v_sub_f32_e32 v90, v90, v148
	v_sub_f32_e32 v89, v89, v148
	v_sub_f32_e32 v88, v88, v148
	v_sub_f32_e32 v87, v87, v148
	v_sub_f32_e32 v86, v86, v148
	v_sub_f32_e32 v85, v85, v148
	v_sub_f32_e32 v84, v84, v148
	v_sub_f32_e32 v83, v83, v148
	v_sub_f32_e32 v82, v82, v148
	v_add_f32_e32 v148, v78, v74
	v_cvt_pk_bf16_f32 v70, v70, v71
	v_cvt_pk_bf16_f32 v71, v72, v73
	v_cvt_pk_bf16_f32 v72, v75, v76
	v_cvt_pk_bf16_f32 v73, v77, v78
	v_mul_f32_e32 v147, v147, v146
	v_xor_b32_e32 v146, 0x80000000, v0
	s_branch .LBB0_200
.LBB0_199:
	v_cvt_pk_bf16_f32 v66, v149, v150
	v_cvt_pk_bf16_f32 v67, v151, v152
	v_cvt_pk_bf16_f32 v68, v153, v164
	v_cvt_pk_bf16_f32 v69, v181, v225
	v_cvt_pk_bf16_f32 v70, v226, v227
	v_cvt_pk_bf16_f32 v71, v239, v240
	v_cvt_pk_bf16_f32 v72, v241, v242
	v_cvt_pk_bf16_f32 v73, v243, v246
.LBB0_200:
	v_mfma_f32_32x32x16_bf16 v[50:65], v[130:133], v[66:69], v[50:65]
	ds_read_b128 v[182:185], v169 offset:32768
	ds_read_b128 v[198:201], v170 offset:32768
	ds_read_b128 v[202:205], v171 offset:32768
	v_exp_f32_e32 v149, v82
	v_exp_f32_e32 v150, v83
	s_add_i32 s0, s97, 0xffffff00
	s_and_b32 s0, s0, 0xf80
	s_cmp_lt_u32 s0, s84
	s_cselect_b64 s[44:45], -1, 0
	s_cmp_lg_u32 s0, s84
	v_mfma_f32_32x32x16_bf16 v[34:49], v[126:129], v[66:69], v[34:49]
	ds_read_b128 v[206:209], v172 offset:32768
	ds_read_b64_tr_b16 v[130:131], v173 offset:24576
	ds_read_b64_tr_b16 v[132:133], v174 offset:24576
	v_exp_f32_e32 v151, v84
	v_exp_f32_e32 v152, v85
	v_mfma_f32_32x32x16_bf16 v[18:33], v[122:125], v[66:69], v[18:33]
	ds_read_b64_tr_b16 v[126:127], v175 offset:24576
	ds_read_b64_tr_b16 v[128:129], v176 offset:24576
	ds_read_b64_tr_b16 v[122:123], v177 offset:24576
	v_exp_f32_e32 v153, v86
	v_exp_f32_e32 v164, v87
	v_mfma_f32_32x32x16_bf16 v[2:17], v[118:121], v[66:69], v[2:17]
	ds_read_b64_tr_b16 v[124:125], v178 offset:24576
	ds_read_b64_tr_b16 v[118:119], v179 offset:24576
	ds_read_b64_tr_b16 v[120:121], v180 offset:24576
	v_exp_f32_e32 v181, v88
	v_exp_f32_e32 v225, v89
	v_lshl_add_u64 v[250:251], v[248:249], 0, s[56:57]
	s_mov_b32 m0, s87
	s_nop 0
	global_load_lds_dwordx4 v[250:251], off
	v_or_b32_e32 v66, s0, v166
	v_sub_u32_e32 v66, v167, v66
	v_cvt_f32_i32_e32 v67, v66
	v_fma_f32 v80, -v158, |v67|, v146
	v_mfma_f32_32x32x16_bf16 v[50:65], v[114:117], v[70:73], v[50:65]
	ds_read_b64_tr_b16 v[114:115], v173 offset:28672
	ds_read_b64_tr_b16 v[116:117], v174 offset:28672
	v_exp_f32_e32 v226, v90
	v_exp_f32_e32 v227, v91
	v_mfma_f32_32x32x16_bf16 v[34:49], v[134:137], v[70:73], v[34:49]
	ds_read_b64_tr_b16 v[134:135], v175 offset:28672
	ds_read_b64_tr_b16 v[136:137], v176 offset:28672
	v_exp_f32_e32 v239, v92
	v_exp_f32_e32 v240, v93
	v_mfma_f32_32x32x16_bf16 v[18:33], v[138:141], v[70:73], v[18:33]
	ds_read_b64_tr_b16 v[138:139], v177 offset:28672
	ds_read_b64_tr_b16 v[140:141], v178 offset:28672
	v_exp_f32_e32 v241, v94
	v_exp_f32_e32 v242, v95
	v_mfma_f32_32x32x16_bf16 v[2:17], v[142:145], v[70:73], v[2:17]
	ds_read_b64_tr_b16 v[142:143], v179 offset:28672
	ds_read_b64_tr_b16 v[144:145], v180 offset:28672
	v_exp_f32_e32 v243, v96
	v_exp_f32_e32 v246, v97
	s_cbranch_scc1 .LBB0_202
	v_add_u32_e32 v67, -2, v66
	v_cvt_f32_i32_e32 v67, v67
	v_add_u32_e32 v68, -1, v66
	v_cvt_f32_i32_e32 v68, v68
	v_add_u32_e32 v70, -8, v66
	v_and_b32_e32 v69, 0x7fffffff, v67
	v_add_u32_e32 v67, -3, v66
	v_cvt_f32_i32_e32 v67, v67
	v_cvt_f32_i32_e32 v70, v70
	v_and_b32_e32 v68, 0x7fffffff, v68
	v_pk_fma_f32 v[210:211], v[162:163], v[68:69], v[146:147] op_sel_hi:[1,1,0]
	v_and_b32_e32 v68, 0x7fffffff, v67
	v_add_u32_e32 v67, -10, v66
	v_cvt_f32_i32_e32 v67, v67
	v_and_b32_e32 v69, 0x7fffffff, v70
	v_pk_fma_f32 v[212:213], v[162:163], v[68:69], v[146:147] op_sel_hi:[1,1,0]
	v_add_u32_e32 v68, -9, v66
	v_cvt_f32_i32_e32 v68, v68
	v_and_b32_e32 v69, 0x7fffffff, v67
	v_add_u32_e32 v67, -16, v66
	v_cvt_f32_i32_e32 v67, v67
	v_add_u32_e32 v70, -11, v66
	v_cvt_f32_i32_e32 v70, v70
	v_and_b32_e32 v68, 0x7fffffff, v68
	v_pk_fma_f32 v[214:215], v[162:163], v[68:69], v[146:147] op_sel_hi:[1,1,0]
	v_and_b32_e32 v69, 0x7fffffff, v67
	v_subrev_u32_e32 v67, 18, v66
	v_cvt_f32_i32_e32 v67, v67
	v_and_b32_e32 v68, 0x7fffffff, v70
	v_pk_fma_f32 v[216:217], v[162:163], v[68:69], v[146:147] op_sel_hi:[1,1,0]
	v_subrev_u32_e32 v68, 17, v66
	v_cvt_f32_i32_e32 v68, v68
	v_and_b32_e32 v69, 0x7fffffff, v67
	v_subrev_u32_e32 v67, 24, v66
	v_subrev_u32_e32 v70, 19, v66
	v_cvt_f32_i32_e32 v67, v67
	v_cvt_f32_i32_e32 v70, v70
	v_and_b32_e32 v68, 0x7fffffff, v68
	v_pk_fma_f32 v[218:219], v[162:163], v[68:69], v[146:147] op_sel_hi:[1,1,0]
	v_and_b32_e32 v69, 0x7fffffff, v67
	v_and_b32_e32 v68, 0x7fffffff, v70
	v_pk_fma_f32 v[220:221], v[162:163], v[68:69], v[146:147] op_sel_hi:[1,1,0]
	v_subrev_u32_e32 v67, 26, v66
	v_subrev_u32_e32 v68, 25, v66
	v_cvt_f32_i32_e32 v67, v67
	v_cvt_f32_i32_e32 v68, v68
	v_subrev_u32_e32 v66, 27, v66
	v_cvt_f32_i32_e32 v69, v66
	v_and_b32_e32 v67, 0x7fffffff, v67
	v_and_b32_e32 v66, 0x7fffffff, v68
	v_mov_b32_e32 v81, v210
	v_pk_fma_f32 v[222:223], v[162:163], v[66:67], v[146:147] op_sel_hi:[1,1,0]
	v_fma_f32 v224, -v158, |v69|, v146
	v_mov_b64_e32 v[66:67], v[80:81]
	v_mov_b64_e32 v[68:69], v[82:83]
	v_mov_b64_e32 v[70:71], v[84:85]
	v_mov_b64_e32 v[72:73], v[86:87]
	v_mov_b64_e32 v[74:75], v[88:89]
	v_mov_b64_e32 v[76:77], v[90:91]
	v_mov_b64_e32 v[78:79], v[92:93]
	v_mov_b64_e32 v[80:81], v[94:95]
	v_mov_b32_e32 v68, v211
	v_mov_b32_e32 v69, v212
	v_mov_b32_e32 v70, v213
	v_mov_b32_e32 v71, v214
	v_mov_b32_e32 v72, v215
	v_mov_b32_e32 v73, v216
	v_mov_b32_e32 v74, v217
	v_mov_b32_e32 v75, v218
	v_mov_b32_e32 v76, v219
	v_mov_b32_e32 v77, v220
	v_mov_b32_e32 v78, v221
	v_mov_b32_e32 v79, v222
	v_mov_b32_e32 v80, v223
	v_mov_b32_e32 v81, v224
	s_branch .LBB0_203

.LBB0_203:
	v_lshl_add_u64 v[250:251], v[248:249], 0, s[68:69]
	s_mov_b32 m0, s86
	s_nop 0
	global_load_lds_dwordx4 v[250:251], off
	v_add_f32_e32 v147, v148, v147
	s_waitcnt lgkmcnt(0)
	v_mfma_f32_32x32x16_bf16 v[66:81], v[182:185], v[98:101], v[66:81]
	v_add_f32_e32 v148, 0, v149
	v_add_f32_e32 v148, v150, v148
	v_mfma_f32_32x32x16_bf16 v[66:81], v[198:201], v[102:105], v[66:81]
	v_add_f32_e32 v148, v151, v148
	v_add_f32_e32 v148, v152, v148
	v_add_f32_e32 v148, v153, v148
	v_mfma_f32_32x32x16_bf16 v[66:81], v[202:205], v[106:109], v[66:81]
	v_add_f32_e32 v148, v164, v148
	v_add_f32_e32 v148, v181, v148
	v_add_f32_e32 v148, v225, v148
	v_add_f32_e32 v148, v226, v148
	v_add_f32_e32 v148, v227, v148
	v_mfma_f32_32x32x16_bf16 v[66:81], v[206:209], v[110:113], v[66:81]
	v_add_f32_e32 v148, v239, v148
	v_add_f32_e32 v148, v240, v148
	v_add_f32_e32 v148, v241, v148
	v_add_f32_e32 v148, v242, v148
	v_add_f32_e32 v148, v243, v148
	v_add_f32_e32 v148, v246, v148
	v_cmp_nge_f32_e32 vcc, s12, v148
	s_cbranch_vccz .LBB0_205
	v_max_f32_e32 v146, v83, v83
	v_max_f32_e32 v148, v82, v82
	v_max_f32_e32 v146, v148, v146
	v_max3_f32 v146, v146, v84, v85
	v_max3_f32 v146, v146, v86, v87
	v_max3_f32 v146, v146, v88, v89
	v_max3_f32 v146, v146, v90, v91
	v_max3_f32 v146, v146, v92, v93
	v_max3_f32 v146, v146, v94, v95
	v_max3_f32 v146, v146, v96, v97
	ds_bpermute_b32 v148, v159, v146
	s_waitcnt lgkmcnt(0)
	v_max3_f32 v148, v146, v148, 0
	v_sub_f32_e32 v82, v82, v148
	v_exp_f32_e32 v82, v82
	v_sub_f32_e32 v83, v83, v148
	v_exp_f32_e32 v83, v83
	v_sub_f32_e32 v84, v84, v148
	v_exp_f32_e32 v84, v84
	v_sub_f32_e32 v85, v85, v148
	v_exp_f32_e32 v85, v85
	v_sub_f32_e32 v86, v86, v148
	v_sub_f32_e32 v87, v87, v148
	v_add_f32_e32 v149, 0, v82
	v_exp_f32_e32 v86, v86
	v_exp_f32_e32 v87, v87
	v_add_f32_e32 v149, v83, v149
	v_sub_f32_e32 v88, v88, v148
	v_sub_f32_e32 v89, v89, v148
	v_add_f32_e32 v149, v84, v149
	v_exp_f32_e32 v88, v88
	v_exp_f32_e32 v89, v89
	v_add_f32_e32 v149, v85, v149
	v_add_f32_e32 v149, v86, v149
	v_cvt_pk_bf16_f32 v82, v82, v83
	v_cvt_pk_bf16_f32 v83, v84, v85
	v_cvt_pk_bf16_f32 v84, v86, v87
	v_sub_f32_e32 v86, v90, v148
	v_add_f32_e32 v149, v87, v149
	v_exp_f32_e32 v86, v86
	v_sub_f32_e32 v87, v91, v148
	v_add_f32_e32 v149, v88, v149
	v_cvt_pk_bf16_f32 v85, v88, v89
	v_exp_f32_e32 v87, v87
	v_sub_f32_e32 v88, v92, v148
	v_add_f32_e32 v149, v89, v149
	v_exp_f32_e32 v88, v88
	v_sub_f32_e32 v89, v93, v148
	v_exp_f32_e32 v89, v89
	v_sub_f32_e32 v91, v94, v148
	v_add_f32_e32 v90, v86, v149
	v_exp_f32_e32 v91, v91
	v_sub_f32_e32 v92, v95, v148
	v_add_f32_e32 v90, v87, v90
	v_exp_f32_e32 v92, v92
	v_sub_f32_e32 v93, v96, v148
	v_add_f32_e32 v90, v88, v90
	v_exp_f32_e32 v93, v93
	v_sub_f32_e32 v94, v97, v148
	v_exp_f32_e64 v146, -v148
	v_add_f32_e32 v90, v89, v90
	v_exp_f32_e32 v94, v94
	v_add_f32_e32 v90, v91, v90
	v_add_f32_e32 v90, v92, v90
	v_add_f32_e32 v0, v0, v148
	v_add_f32_e32 v90, v93, v90
	v_pk_mul_f32 v[64:65], v[64:65], v[146:147] op_sel_hi:[1,0]
	v_pk_mul_f32 v[62:63], v[62:63], v[146:147] op_sel_hi:[1,0]
	v_pk_mul_f32 v[60:61], v[60:61], v[146:147] op_sel_hi:[1,0]
	v_pk_mul_f32 v[58:59], v[58:59], v[146:147] op_sel_hi:[1,0]
	v_pk_mul_f32 v[56:57], v[56:57], v[146:147] op_sel_hi:[1,0]
	v_pk_mul_f32 v[54:55], v[54:55], v[146:147] op_sel_hi:[1,0]
	v_pk_mul_f32 v[52:53], v[52:53], v[146:147] op_sel_hi:[1,0]
	v_pk_mul_f32 v[50:51], v[50:51], v[146:147] op_sel_hi:[1,0]
	v_pk_mul_f32 v[48:49], v[48:49], v[146:147] op_sel_hi:[1,0]
	v_pk_mul_f32 v[46:47], v[46:47], v[146:147] op_sel_hi:[1,0]
	v_pk_mul_f32 v[44:45], v[44:45], v[146:147] op_sel_hi:[1,0]
	v_pk_mul_f32 v[42:43], v[42:43], v[146:147] op_sel_hi:[1,0]
	v_pk_mul_f32 v[40:41], v[40:41], v[146:147] op_sel_hi:[1,0]
	v_pk_mul_f32 v[38:39], v[38:39], v[146:147] op_sel_hi:[1,0]
	v_pk_mul_f32 v[36:37], v[36:37], v[146:147] op_sel_hi:[1,0]
	v_pk_mul_f32 v[34:35], v[34:35], v[146:147] op_sel_hi:[1,0]
	v_pk_mul_f32 v[32:33], v[32:33], v[146:147] op_sel_hi:[1,0]
	v_pk_mul_f32 v[30:31], v[30:31], v[146:147] op_sel_hi:[1,0]
	v_pk_mul_f32 v[28:29], v[28:29], v[146:147] op_sel_hi:[1,0]
	v_pk_mul_f32 v[26:27], v[26:27], v[146:147] op_sel_hi:[1,0]
	v_pk_mul_f32 v[24:25], v[24:25], v[146:147] op_sel_hi:[1,0]
	v_pk_mul_f32 v[22:23], v[22:23], v[146:147] op_sel_hi:[1,0]
	v_pk_mul_f32 v[20:21], v[20:21], v[146:147] op_sel_hi:[1,0]
	v_pk_mul_f32 v[18:19], v[18:19], v[146:147] op_sel_hi:[1,0]
	v_pk_mul_f32 v[16:17], v[16:17], v[146:147] op_sel_hi:[1,0]
	v_pk_mul_f32 v[14:15], v[14:15], v[146:147] op_sel_hi:[1,0]
	v_pk_mul_f32 v[12:13], v[12:13], v[146:147] op_sel_hi:[1,0]
	v_pk_mul_f32 v[10:11], v[10:11], v[146:147] op_sel_hi:[1,0]
	v_pk_mul_f32 v[8:9], v[8:9], v[146:147] op_sel_hi:[1,0]
	v_pk_mul_f32 v[6:7], v[6:7], v[146:147] op_sel_hi:[1,0]
	v_pk_mul_f32 v[4:5], v[4:5], v[146:147] op_sel_hi:[1,0]
	v_pk_mul_f32 v[2:3], v[2:3], v[146:147] op_sel_hi:[1,0]
	v_sub_f32_e32 v81, v81, v148
	v_sub_f32_e32 v80, v80, v148
	v_sub_f32_e32 v79, v79, v148
	v_sub_f32_e32 v78, v78, v148
	v_sub_f32_e32 v77, v77, v148
	v_sub_f32_e32 v76, v76, v148
	v_sub_f32_e32 v75, v75, v148
	v_sub_f32_e32 v74, v74, v148
	v_sub_f32_e32 v73, v73, v148
	v_sub_f32_e32 v72, v72, v148
	v_sub_f32_e32 v71, v71, v148
	v_sub_f32_e32 v70, v70, v148
	v_sub_f32_e32 v69, v69, v148
	v_sub_f32_e32 v68, v68, v148
	v_sub_f32_e32 v67, v67, v148
	v_sub_f32_e32 v66, v66, v148
	v_add_f32_e32 v148, v94, v90
	v_cvt_pk_bf16_f32 v86, v86, v87
	v_cvt_pk_bf16_f32 v87, v88, v89
	v_cvt_pk_bf16_f32 v88, v91, v92
	v_cvt_pk_bf16_f32 v89, v93, v94
	v_mul_f32_e32 v147, v147, v146
	v_xor_b32_e32 v146, 0x80000000, v0
	s_branch .LBB0_206

.LBB0_206:
	v_mfma_f32_32x32x16_bf16 v[50:65], v[130:133], v[82:85], v[50:65]
	ds_read_b128 v[182:185], v169 offset:40960
	ds_read_b128 v[198:201], v170 offset:40960
	ds_read_b128 v[202:205], v171 offset:40960
	v_exp_f32_e32 v149, v66
	v_exp_f32_e32 v150, v67
	s_or_b32 s0, s0, 32
	s_cmp_lt_u32 s0, s84
	s_cselect_b64 s[44:45], -1, 0
	s_cmp_lg_u32 s0, s84
	v_mfma_f32_32x32x16_bf16 v[34:49], v[126:129], v[82:85], v[34:49]
	ds_read_b128 v[206:209], v172 offset:40960
	ds_read_b64_tr_b16 v[130:131], v173 offset:32768
	ds_read_b64_tr_b16 v[132:133], v174 offset:32768
	v_exp_f32_e32 v151, v68
	v_exp_f32_e32 v152, v69
	v_mfma_f32_32x32x16_bf16 v[18:33], v[122:125], v[82:85], v[18:33]
	ds_read_b64_tr_b16 v[126:127], v175 offset:32768
	ds_read_b64_tr_b16 v[128:129], v176 offset:32768
	ds_read_b64_tr_b16 v[122:123], v177 offset:32768
	v_exp_f32_e32 v153, v70
	v_exp_f32_e32 v164, v71
	v_mfma_f32_32x32x16_bf16 v[2:17], v[118:121], v[82:85], v[2:17]
	ds_read_b64_tr_b16 v[124:125], v178 offset:32768
	ds_read_b64_tr_b16 v[118:119], v179 offset:32768
	ds_read_b64_tr_b16 v[120:121], v180 offset:32768
	v_exp_f32_e32 v181, v72
	v_exp_f32_e32 v225, v73
	v_lshl_add_u64 v[250:251], v[248:249], 0, s[46:47]
	s_mov_b32 m0, s88
	s_nop 0
	global_load_lds_dwordx4 v[250:251], off
	v_or_b32_e32 v82, s0, v166
	v_sub_u32_e32 v82, v167, v82
	v_cvt_f32_i32_e32 v83, v82
	v_fma_f32 v96, -v158, |v83|, v146
	v_mfma_f32_32x32x16_bf16 v[50:65], v[114:117], v[86:89], v[50:65]
	ds_read_b64_tr_b16 v[114:115], v173 offset:36864
	ds_read_b64_tr_b16 v[116:117], v174 offset:36864
	v_exp_f32_e32 v226, v74
	v_exp_f32_e32 v227, v75
	v_mfma_f32_32x32x16_bf16 v[34:49], v[134:137], v[86:89], v[34:49]
	ds_read_b64_tr_b16 v[134:135], v175 offset:36864
	ds_read_b64_tr_b16 v[136:137], v176 offset:36864
	v_exp_f32_e32 v239, v76
	v_exp_f32_e32 v240, v77
	v_mfma_f32_32x32x16_bf16 v[18:33], v[138:141], v[86:89], v[18:33]
	ds_read_b64_tr_b16 v[138:139], v177 offset:36864
	ds_read_b64_tr_b16 v[140:141], v178 offset:36864
	v_exp_f32_e32 v241, v78
	v_exp_f32_e32 v242, v79
	v_mfma_f32_32x32x16_bf16 v[2:17], v[142:145], v[86:89], v[2:17]
	ds_read_b64_tr_b16 v[142:143], v179 offset:36864
	ds_read_b64_tr_b16 v[144:145], v180 offset:36864
	v_exp_f32_e32 v243, v80
	v_exp_f32_e32 v246, v81
	s_cbranch_scc1 .LBB0_208
	v_add_u32_e32 v83, -2, v82
	v_cvt_f32_i32_e32 v83, v83
	v_add_u32_e32 v84, -1, v82
	v_cvt_f32_i32_e32 v84, v84
	v_add_u32_e32 v86, -8, v82
	v_and_b32_e32 v85, 0x7fffffff, v83
	v_add_u32_e32 v83, -3, v82
	v_cvt_f32_i32_e32 v83, v83
	v_cvt_f32_i32_e32 v86, v86
	v_and_b32_e32 v84, 0x7fffffff, v84
	v_pk_fma_f32 v[210:211], v[162:163], v[84:85], v[146:147] op_sel_hi:[1,1,0]
	v_and_b32_e32 v84, 0x7fffffff, v83
	v_add_u32_e32 v83, -10, v82
	v_cvt_f32_i32_e32 v83, v83
	v_and_b32_e32 v85, 0x7fffffff, v86
	v_pk_fma_f32 v[212:213], v[162:163], v[84:85], v[146:147] op_sel_hi:[1,1,0]
	v_add_u32_e32 v84, -9, v82
	v_cvt_f32_i32_e32 v84, v84
	v_and_b32_e32 v85, 0x7fffffff, v83
	v_add_u32_e32 v83, -16, v82
	v_cvt_f32_i32_e32 v83, v83
	v_add_u32_e32 v86, -11, v82
	v_cvt_f32_i32_e32 v86, v86
	v_and_b32_e32 v84, 0x7fffffff, v84
	v_pk_fma_f32 v[214:215], v[162:163], v[84:85], v[146:147] op_sel_hi:[1,1,0]
	v_and_b32_e32 v85, 0x7fffffff, v83
	v_subrev_u32_e32 v83, 18, v82
	v_cvt_f32_i32_e32 v83, v83
	v_and_b32_e32 v84, 0x7fffffff, v86
	v_pk_fma_f32 v[216:217], v[162:163], v[84:85], v[146:147] op_sel_hi:[1,1,0]
	v_subrev_u32_e32 v84, 17, v82
	v_cvt_f32_i32_e32 v84, v84
	v_and_b32_e32 v85, 0x7fffffff, v83
	v_subrev_u32_e32 v83, 24, v82
	v_subrev_u32_e32 v86, 19, v82
	v_cvt_f32_i32_e32 v83, v83
	v_cvt_f32_i32_e32 v86, v86
	v_and_b32_e32 v84, 0x7fffffff, v84
	v_pk_fma_f32 v[218:219], v[162:163], v[84:85], v[146:147] op_sel_hi:[1,1,0]
	v_and_b32_e32 v85, 0x7fffffff, v83
	v_and_b32_e32 v84, 0x7fffffff, v86
	v_pk_fma_f32 v[220:221], v[162:163], v[84:85], v[146:147] op_sel_hi:[1,1,0]
	v_subrev_u32_e32 v83, 26, v82
	v_subrev_u32_e32 v84, 25, v82
	v_cvt_f32_i32_e32 v83, v83
	v_cvt_f32_i32_e32 v84, v84
	v_subrev_u32_e32 v82, 27, v82
	v_cvt_f32_i32_e32 v85, v82
	v_and_b32_e32 v83, 0x7fffffff, v83
	v_and_b32_e32 v82, 0x7fffffff, v84
	v_mov_b32_e32 v97, v210
	v_pk_fma_f32 v[222:223], v[162:163], v[82:83], v[146:147] op_sel_hi:[1,1,0]
	v_fma_f32 v224, -v158, |v85|, v146
	v_mov_b64_e32 v[82:83], v[96:97]
	v_mov_b64_e32 v[84:85], v[98:99]
	v_mov_b64_e32 v[86:87], v[100:101]
	v_mov_b64_e32 v[88:89], v[102:103]
	v_mov_b64_e32 v[90:91], v[104:105]
	v_mov_b64_e32 v[92:93], v[106:107]
	v_mov_b64_e32 v[94:95], v[108:109]
	v_mov_b64_e32 v[96:97], v[110:111]
	v_mov_b32_e32 v84, v211
	v_mov_b32_e32 v85, v212
	v_mov_b32_e32 v86, v213
	v_mov_b32_e32 v87, v214
	v_mov_b32_e32 v88, v215
	v_mov_b32_e32 v89, v216
	v_mov_b32_e32 v90, v217
	v_mov_b32_e32 v91, v218
	v_mov_b32_e32 v92, v219
	v_mov_b32_e32 v93, v220
	v_mov_b32_e32 v94, v221
	v_mov_b32_e32 v95, v222
	v_mov_b32_e32 v96, v223
	v_mov_b32_e32 v97, v224
	s_mov_b64 s[44:45], -1
	s_and_b64 vcc, exec, s[42:43]
	s_cbranch_vccnz .LBB0_209
	s_branch .LBB0_210
.LBB0_208:
	v_cndmask_b32_e64 v244, -v158, v158, s[44:45]
	v_fma_f32 v82, 0, v244, v96
	v_add_f32_e32 v83, v244, v96
	v_pk_fma_f32 v[84:85], v[244:245], s[26:27], v[96:97] op_sel_hi:[0,1,0]
	v_pk_fma_f32 v[86:87], v[244:245], s[28:29], v[96:97] op_sel_hi:[0,1,0]
	v_pk_fma_f32 v[88:89], v[244:245], s[30:31], v[96:97] op_sel_hi:[0,1,0]
	v_pk_fma_f32 v[90:91], v[244:245], s[34:35], v[96:97] op_sel_hi:[0,1,0]
	v_pk_fma_f32 v[92:93], v[244:245], s[36:37], v[96:97] op_sel_hi:[0,1,0]
	v_pk_fma_f32 v[94:95], v[244:245], s[14:15], v[96:97] op_sel_hi:[0,1,0]
	v_pk_fma_f32 v[96:97], v[244:245], s[10:11], v[96:97] op_sel_hi:[0,1,0]
	s_mov_b64 s[44:45], -1
	s_and_b64 vcc, exec, s[42:43]
	s_cbranch_vccz .LBB0_210

.LBB0_212:
	s_barrier
	s_cmp_gt_u32 s98, 58
	s_cselect_b64 s[44:45], -1, 0
	s_sub_i32 s0, s97, 64
	s_and_b32 s0, s0, 0xfc0
	s_mul_i32 s18, s0, 0x1200
	v_lshl_add_u64 v[248:249], v[160:161], 0, s[18:19]
	v_lshl_add_u64 v[250:251], v[248:249], 0, s[22:23]
	s_mov_b32 m0, s89
	s_nop 0
	global_load_lds_dwordx4 v[250:251], off

.LBB0_217:
	v_mfma_f32_32x32x16_bf16 v[50:65], v[130:133], v[66:69], v[50:65]
	ds_read_b128 v[182:185], v169 offset:49152
	ds_read_b128 v[198:201], v170 offset:49152
	ds_read_b128 v[202:205], v171 offset:49152
	v_exp_f32_e32 v149, v82
	v_exp_f32_e32 v150, v83
	s_cmp_lt_u32 s99, s84
	s_cselect_b64 s[48:49], -1, 0
	s_cmp_lg_u32 s99, s84
	v_mfma_f32_32x32x16_bf16 v[34:49], v[126:129], v[66:69], v[34:49]
	ds_read_b128 v[206:209], v172 offset:49152
	ds_read_b64_tr_b16 v[130:131], v173 offset:40960
	ds_read_b64_tr_b16 v[132:133], v174 offset:40960
	v_exp_f32_e32 v151, v84
	v_exp_f32_e32 v152, v85
	v_mfma_f32_32x32x16_bf16 v[18:33], v[122:125], v[66:69], v[18:33]
	ds_read_b64_tr_b16 v[126:127], v175 offset:40960
	ds_read_b64_tr_b16 v[128:129], v176 offset:40960
	ds_read_b64_tr_b16 v[122:123], v177 offset:40960
	v_exp_f32_e32 v153, v86
	v_exp_f32_e32 v164, v87
	v_mfma_f32_32x32x16_bf16 v[2:17], v[118:121], v[66:69], v[2:17]
	ds_read_b64_tr_b16 v[124:125], v178 offset:40960
	ds_read_b64_tr_b16 v[118:119], v179 offset:40960
	ds_read_b64_tr_b16 v[120:121], v180 offset:40960
	v_exp_f32_e32 v181, v88
	v_exp_f32_e32 v225, v89
	v_lshl_add_u64 v[250:251], v[248:249], 0, s[56:57]
	s_mov_b32 m0, s91
	s_nop 0
	global_load_lds_dwordx4 v[250:251], off
	v_or_b32_e32 v66, s99, v166
	v_sub_u32_e32 v66, v167, v66
	v_cvt_f32_i32_e32 v67, v66
	v_fma_f32 v80, -v158, |v67|, v146
	v_mfma_f32_32x32x16_bf16 v[50:65], v[114:117], v[70:73], v[50:65]
	ds_read_b64_tr_b16 v[114:115], v173 offset:45056
	ds_read_b64_tr_b16 v[116:117], v174 offset:45056
	v_exp_f32_e32 v226, v90
	v_exp_f32_e32 v227, v91
	v_mfma_f32_32x32x16_bf16 v[34:49], v[134:137], v[70:73], v[34:49]
	ds_read_b64_tr_b16 v[134:135], v175 offset:45056
	ds_read_b64_tr_b16 v[136:137], v176 offset:45056
	v_exp_f32_e32 v239, v92
	v_exp_f32_e32 v240, v93
	v_mfma_f32_32x32x16_bf16 v[18:33], v[138:141], v[70:73], v[18:33]
	ds_read_b64_tr_b16 v[138:139], v177 offset:45056
	ds_read_b64_tr_b16 v[140:141], v178 offset:45056
	v_exp_f32_e32 v241, v94
	v_exp_f32_e32 v242, v95
	v_mfma_f32_32x32x16_bf16 v[2:17], v[142:145], v[70:73], v[2:17]
	ds_read_b64_tr_b16 v[142:143], v179 offset:45056
	ds_read_b64_tr_b16 v[144:145], v180 offset:45056
	v_exp_f32_e32 v243, v96
	v_exp_f32_e32 v246, v97
	s_cbranch_scc1 .LBB0_219
	v_add_u32_e32 v67, -2, v66
	v_cvt_f32_i32_e32 v67, v67
	v_add_u32_e32 v68, -1, v66
	v_cvt_f32_i32_e32 v68, v68
	v_add_u32_e32 v70, -8, v66
	v_and_b32_e32 v69, 0x7fffffff, v67
	v_add_u32_e32 v67, -3, v66
	v_cvt_f32_i32_e32 v67, v67
	v_cvt_f32_i32_e32 v70, v70
	v_and_b32_e32 v68, 0x7fffffff, v68
	v_pk_fma_f32 v[210:211], v[162:163], v[68:69], v[146:147] op_sel_hi:[1,1,0]
	v_and_b32_e32 v68, 0x7fffffff, v67
	v_add_u32_e32 v67, -10, v66
	v_cvt_f32_i32_e32 v67, v67
	v_and_b32_e32 v69, 0x7fffffff, v70
	v_pk_fma_f32 v[212:213], v[162:163], v[68:69], v[146:147] op_sel_hi:[1,1,0]
	v_add_u32_e32 v68, -9, v66
	v_cvt_f32_i32_e32 v68, v68
	v_and_b32_e32 v69, 0x7fffffff, v67
	v_add_u32_e32 v67, -16, v66
	v_cvt_f32_i32_e32 v67, v67
	v_add_u32_e32 v70, -11, v66
	v_cvt_f32_i32_e32 v70, v70
	v_and_b32_e32 v68, 0x7fffffff, v68
	v_pk_fma_f32 v[214:215], v[162:163], v[68:69], v[146:147] op_sel_hi:[1,1,0]
	v_and_b32_e32 v69, 0x7fffffff, v67
	v_subrev_u32_e32 v67, 18, v66
	v_cvt_f32_i32_e32 v67, v67
	v_and_b32_e32 v68, 0x7fffffff, v70
	v_pk_fma_f32 v[216:217], v[162:163], v[68:69], v[146:147] op_sel_hi:[1,1,0]
	v_subrev_u32_e32 v68, 17, v66
	v_cvt_f32_i32_e32 v68, v68
	v_and_b32_e32 v69, 0x7fffffff, v67
	v_subrev_u32_e32 v67, 24, v66
	v_subrev_u32_e32 v70, 19, v66
	v_cvt_f32_i32_e32 v67, v67
	v_cvt_f32_i32_e32 v70, v70
	v_and_b32_e32 v68, 0x7fffffff, v68
	v_pk_fma_f32 v[218:219], v[162:163], v[68:69], v[146:147] op_sel_hi:[1,1,0]
	v_and_b32_e32 v69, 0x7fffffff, v67
	v_and_b32_e32 v68, 0x7fffffff, v70
	v_pk_fma_f32 v[220:221], v[162:163], v[68:69], v[146:147] op_sel_hi:[1,1,0]
	v_subrev_u32_e32 v67, 26, v66
	v_subrev_u32_e32 v68, 25, v66
	v_cvt_f32_i32_e32 v67, v67
	v_cvt_f32_i32_e32 v68, v68
	v_subrev_u32_e32 v66, 27, v66
	v_cvt_f32_i32_e32 v69, v66
	v_and_b32_e32 v67, 0x7fffffff, v67
	v_and_b32_e32 v66, 0x7fffffff, v68
	v_mov_b32_e32 v81, v210
	v_pk_fma_f32 v[222:223], v[162:163], v[66:67], v[146:147] op_sel_hi:[1,1,0]
	v_fma_f32 v224, -v158, |v69|, v146
	v_mov_b64_e32 v[66:67], v[80:81]
	v_mov_b64_e32 v[68:69], v[82:83]
	v_mov_b64_e32 v[70:71], v[84:85]
	v_mov_b64_e32 v[72:73], v[86:87]
	v_mov_b64_e32 v[74:75], v[88:89]
	v_mov_b64_e32 v[76:77], v[90:91]
	v_mov_b64_e32 v[78:79], v[92:93]
	v_mov_b64_e32 v[80:81], v[94:95]
	v_mov_b32_e32 v68, v211
	v_mov_b32_e32 v69, v212
	v_mov_b32_e32 v70, v213
	v_mov_b32_e32 v71, v214
	v_mov_b32_e32 v72, v215
	v_mov_b32_e32 v73, v216
	v_mov_b32_e32 v74, v217
	v_mov_b32_e32 v75, v218
	v_mov_b32_e32 v76, v219
	v_mov_b32_e32 v77, v220
	v_mov_b32_e32 v78, v221
	v_mov_b32_e32 v79, v222
	v_mov_b32_e32 v80, v223
	v_mov_b32_e32 v81, v224
	s_branch .LBB0_220

.LBB0_220:
	v_lshl_add_u64 v[250:251], v[248:249], 0, s[68:69]
	s_mov_b32 m0, s90
	s_nop 0
	global_load_lds_dwordx4 v[250:251], off
	v_add_f32_e32 v147, v148, v147
	s_waitcnt lgkmcnt(0)
	v_mfma_f32_32x32x16_bf16 v[66:81], v[182:185], v[98:101], v[66:81]
	v_add_f32_e32 v148, 0, v149
	v_add_f32_e32 v148, v150, v148
	v_mfma_f32_32x32x16_bf16 v[66:81], v[198:201], v[102:105], v[66:81]
	v_add_f32_e32 v148, v151, v148
	v_add_f32_e32 v148, v152, v148
	v_add_f32_e32 v148, v153, v148
	v_mfma_f32_32x32x16_bf16 v[66:81], v[202:205], v[106:109], v[66:81]
	v_add_f32_e32 v148, v164, v148
	v_add_f32_e32 v148, v181, v148
	v_add_f32_e32 v148, v225, v148
	v_add_f32_e32 v148, v226, v148
	v_add_f32_e32 v148, v227, v148
	v_mfma_f32_32x32x16_bf16 v[66:81], v[206:209], v[110:113], v[66:81]
	v_add_f32_e32 v148, v239, v148
	v_add_f32_e32 v148, v240, v148
	v_add_f32_e32 v148, v241, v148
	v_add_f32_e32 v148, v242, v148
	v_add_f32_e32 v148, v243, v148
	v_add_f32_e32 v148, v246, v148
	v_cmp_nge_f32_e32 vcc, s12, v148
	s_cbranch_vccz .LBB0_222
	v_max_f32_e32 v146, v83, v83
	v_max_f32_e32 v148, v82, v82
	v_max_f32_e32 v146, v148, v146
	v_max3_f32 v146, v146, v84, v85
	v_max3_f32 v146, v146, v86, v87
	v_max3_f32 v146, v146, v88, v89
	v_max3_f32 v146, v146, v90, v91
	v_max3_f32 v146, v146, v92, v93
	v_max3_f32 v146, v146, v94, v95
	v_max3_f32 v146, v146, v96, v97
	ds_bpermute_b32 v148, v159, v146
	s_waitcnt lgkmcnt(0)
	v_max3_f32 v148, v146, v148, 0
	v_sub_f32_e32 v82, v82, v148
	v_exp_f32_e32 v82, v82
	v_sub_f32_e32 v83, v83, v148
	v_exp_f32_e32 v83, v83
	v_sub_f32_e32 v84, v84, v148
	v_exp_f32_e32 v84, v84
	v_sub_f32_e32 v85, v85, v148
	v_exp_f32_e32 v85, v85
	v_sub_f32_e32 v86, v86, v148
	v_sub_f32_e32 v87, v87, v148
	v_add_f32_e32 v149, 0, v82
	v_exp_f32_e32 v86, v86
	v_exp_f32_e32 v87, v87
	v_add_f32_e32 v149, v83, v149
	v_sub_f32_e32 v88, v88, v148
	v_sub_f32_e32 v89, v89, v148
	v_add_f32_e32 v149, v84, v149
	v_exp_f32_e32 v88, v88
	v_exp_f32_e32 v89, v89
	v_add_f32_e32 v149, v85, v149
	v_add_f32_e32 v149, v86, v149
	v_cvt_pk_bf16_f32 v82, v82, v83
	v_cvt_pk_bf16_f32 v83, v84, v85
	v_cvt_pk_bf16_f32 v84, v86, v87
	v_sub_f32_e32 v86, v90, v148
	v_add_f32_e32 v149, v87, v149
	v_exp_f32_e32 v86, v86
	v_sub_f32_e32 v87, v91, v148
	v_add_f32_e32 v149, v88, v149
	v_cvt_pk_bf16_f32 v85, v88, v89
	v_exp_f32_e32 v87, v87
	v_sub_f32_e32 v88, v92, v148
	v_add_f32_e32 v149, v89, v149
	v_exp_f32_e32 v88, v88
	v_sub_f32_e32 v89, v93, v148
	v_exp_f32_e32 v89, v89
	v_sub_f32_e32 v91, v94, v148
	v_add_f32_e32 v90, v86, v149
	v_exp_f32_e32 v91, v91
	v_sub_f32_e32 v92, v95, v148
	v_add_f32_e32 v90, v87, v90
	v_exp_f32_e32 v92, v92
	v_sub_f32_e32 v93, v96, v148
	v_add_f32_e32 v90, v88, v90
	v_exp_f32_e32 v93, v93
	v_sub_f32_e32 v94, v97, v148
	v_exp_f32_e64 v146, -v148
	v_add_f32_e32 v90, v89, v90
	v_exp_f32_e32 v94, v94
	v_add_f32_e32 v90, v91, v90
	v_add_f32_e32 v90, v92, v90
	v_add_f32_e32 v0, v0, v148
	v_add_f32_e32 v90, v93, v90
	v_pk_mul_f32 v[64:65], v[64:65], v[146:147] op_sel_hi:[1,0]
	v_pk_mul_f32 v[62:63], v[62:63], v[146:147] op_sel_hi:[1,0]
	v_pk_mul_f32 v[60:61], v[60:61], v[146:147] op_sel_hi:[1,0]
	v_pk_mul_f32 v[58:59], v[58:59], v[146:147] op_sel_hi:[1,0]
	v_pk_mul_f32 v[56:57], v[56:57], v[146:147] op_sel_hi:[1,0]
	v_pk_mul_f32 v[54:55], v[54:55], v[146:147] op_sel_hi:[1,0]
	v_pk_mul_f32 v[52:53], v[52:53], v[146:147] op_sel_hi:[1,0]
	v_pk_mul_f32 v[50:51], v[50:51], v[146:147] op_sel_hi:[1,0]
	v_pk_mul_f32 v[48:49], v[48:49], v[146:147] op_sel_hi:[1,0]
	v_pk_mul_f32 v[46:47], v[46:47], v[146:147] op_sel_hi:[1,0]
	v_pk_mul_f32 v[44:45], v[44:45], v[146:147] op_sel_hi:[1,0]
	v_pk_mul_f32 v[42:43], v[42:43], v[146:147] op_sel_hi:[1,0]
	v_pk_mul_f32 v[40:41], v[40:41], v[146:147] op_sel_hi:[1,0]
	v_pk_mul_f32 v[38:39], v[38:39], v[146:147] op_sel_hi:[1,0]
	v_pk_mul_f32 v[36:37], v[36:37], v[146:147] op_sel_hi:[1,0]
	v_pk_mul_f32 v[34:35], v[34:35], v[146:147] op_sel_hi:[1,0]
	v_pk_mul_f32 v[32:33], v[32:33], v[146:147] op_sel_hi:[1,0]
	v_pk_mul_f32 v[30:31], v[30:31], v[146:147] op_sel_hi:[1,0]
	v_pk_mul_f32 v[28:29], v[28:29], v[146:147] op_sel_hi:[1,0]
	v_pk_mul_f32 v[26:27], v[26:27], v[146:147] op_sel_hi:[1,0]
	v_pk_mul_f32 v[24:25], v[24:25], v[146:147] op_sel_hi:[1,0]
	v_pk_mul_f32 v[22:23], v[22:23], v[146:147] op_sel_hi:[1,0]
	v_pk_mul_f32 v[20:21], v[20:21], v[146:147] op_sel_hi:[1,0]
	v_pk_mul_f32 v[18:19], v[18:19], v[146:147] op_sel_hi:[1,0]
	v_pk_mul_f32 v[16:17], v[16:17], v[146:147] op_sel_hi:[1,0]
	v_pk_mul_f32 v[14:15], v[14:15], v[146:147] op_sel_hi:[1,0]
	v_pk_mul_f32 v[12:13], v[12:13], v[146:147] op_sel_hi:[1,0]
	v_pk_mul_f32 v[10:11], v[10:11], v[146:147] op_sel_hi:[1,0]
	v_pk_mul_f32 v[8:9], v[8:9], v[146:147] op_sel_hi:[1,0]
	v_pk_mul_f32 v[6:7], v[6:7], v[146:147] op_sel_hi:[1,0]
	v_pk_mul_f32 v[4:5], v[4:5], v[146:147] op_sel_hi:[1,0]
	v_pk_mul_f32 v[2:3], v[2:3], v[146:147] op_sel_hi:[1,0]
	v_sub_f32_e32 v81, v81, v148
	v_sub_f32_e32 v80, v80, v148
	v_sub_f32_e32 v79, v79, v148
	v_sub_f32_e32 v78, v78, v148
	v_sub_f32_e32 v77, v77, v148
	v_sub_f32_e32 v76, v76, v148
	v_sub_f32_e32 v75, v75, v148
	v_sub_f32_e32 v74, v74, v148
	v_sub_f32_e32 v73, v73, v148
	v_sub_f32_e32 v72, v72, v148
	v_sub_f32_e32 v71, v71, v148
	v_sub_f32_e32 v70, v70, v148
	v_sub_f32_e32 v69, v69, v148
	v_sub_f32_e32 v68, v68, v148
	v_sub_f32_e32 v67, v67, v148
	v_sub_f32_e32 v66, v66, v148
	v_add_f32_e32 v148, v94, v90
	v_cvt_pk_bf16_f32 v86, v86, v87
	v_cvt_pk_bf16_f32 v87, v88, v89
	v_cvt_pk_bf16_f32 v88, v91, v92
	v_cvt_pk_bf16_f32 v89, v93, v94
	v_mul_f32_e32 v147, v147, v146
	v_xor_b32_e32 v146, 0x80000000, v0
	s_branch .LBB0_223

.LBB0_223:
	v_mfma_f32_32x32x16_bf16 v[50:65], v[130:133], v[82:85], v[50:65]
	ds_read_b128 v[182:185], v169 offset:57344
	ds_read_b128 v[198:201], v170 offset:57344
	ds_read_b128 v[202:205], v171 offset:57344
	v_exp_f32_e32 v149, v66
	v_exp_f32_e32 v150, v67
	s_or_b32 s0, s99, 32
	s_cmp_lt_u32 s0, s84
	s_cselect_b64 s[48:49], -1, 0
	s_cmp_lg_u32 s0, s84
	v_mfma_f32_32x32x16_bf16 v[34:49], v[126:129], v[82:85], v[34:49]
	ds_read_b128 v[206:209], v172 offset:57344
	ds_read_b64_tr_b16 v[130:131], v173 offset:49152
	ds_read_b64_tr_b16 v[132:133], v174 offset:49152
	v_exp_f32_e32 v151, v68
	v_exp_f32_e32 v152, v69
	v_mfma_f32_32x32x16_bf16 v[18:33], v[122:125], v[82:85], v[18:33]
	ds_read_b64_tr_b16 v[126:127], v175 offset:49152
	ds_read_b64_tr_b16 v[128:129], v176 offset:49152
	ds_read_b64_tr_b16 v[122:123], v177 offset:49152
	v_exp_f32_e32 v153, v70
	v_exp_f32_e32 v164, v71
	v_mfma_f32_32x32x16_bf16 v[2:17], v[118:121], v[82:85], v[2:17]
	ds_read_b64_tr_b16 v[124:125], v178 offset:49152
	ds_read_b64_tr_b16 v[118:119], v179 offset:49152
	ds_read_b64_tr_b16 v[120:121], v180 offset:49152
	v_exp_f32_e32 v181, v72
	v_exp_f32_e32 v225, v73
	v_lshl_add_u64 v[250:251], v[248:249], 0, s[46:47]
	s_mov_b32 m0, s92
	s_nop 0
	global_load_lds_dwordx4 v[250:251], off
	v_or_b32_e32 v82, s0, v166
	v_sub_u32_e32 v82, v167, v82
	v_cvt_f32_i32_e32 v83, v82
	v_fma_f32 v96, -v158, |v83|, v146
	v_mfma_f32_32x32x16_bf16 v[50:65], v[114:117], v[86:89], v[50:65]
	ds_read_b64_tr_b16 v[114:115], v173 offset:53248
	ds_read_b64_tr_b16 v[116:117], v174 offset:53248
	v_exp_f32_e32 v226, v74
	v_exp_f32_e32 v227, v75
	v_mfma_f32_32x32x16_bf16 v[34:49], v[134:137], v[86:89], v[34:49]
	ds_read_b64_tr_b16 v[134:135], v175 offset:53248
	ds_read_b64_tr_b16 v[136:137], v176 offset:53248
	v_exp_f32_e32 v239, v76
	v_exp_f32_e32 v240, v77
	v_mfma_f32_32x32x16_bf16 v[18:33], v[138:141], v[86:89], v[18:33]
	ds_read_b64_tr_b16 v[138:139], v177 offset:53248
	ds_read_b64_tr_b16 v[140:141], v178 offset:53248
	v_exp_f32_e32 v241, v78
	v_exp_f32_e32 v242, v79
	v_mfma_f32_32x32x16_bf16 v[2:17], v[142:145], v[86:89], v[2:17]
	ds_read_b64_tr_b16 v[142:143], v179 offset:53248
	ds_read_b64_tr_b16 v[144:145], v180 offset:53248
	v_exp_f32_e32 v243, v80
	v_exp_f32_e32 v246, v81
	s_cbranch_scc1 .LBB0_225
	v_add_u32_e32 v83, -2, v82
	v_cvt_f32_i32_e32 v83, v83
	v_add_u32_e32 v84, -1, v82
	v_cvt_f32_i32_e32 v84, v84
	v_add_u32_e32 v86, -8, v82
	v_and_b32_e32 v85, 0x7fffffff, v83
	v_add_u32_e32 v83, -3, v82
	v_cvt_f32_i32_e32 v83, v83
	v_cvt_f32_i32_e32 v86, v86
	v_and_b32_e32 v84, 0x7fffffff, v84
	v_pk_fma_f32 v[210:211], v[162:163], v[84:85], v[146:147] op_sel_hi:[1,1,0]
	v_and_b32_e32 v84, 0x7fffffff, v83
	v_add_u32_e32 v83, -10, v82
	v_cvt_f32_i32_e32 v83, v83
	v_and_b32_e32 v85, 0x7fffffff, v86
	v_pk_fma_f32 v[212:213], v[162:163], v[84:85], v[146:147] op_sel_hi:[1,1,0]
	v_add_u32_e32 v84, -9, v82
	v_cvt_f32_i32_e32 v84, v84
	v_and_b32_e32 v85, 0x7fffffff, v83
	v_add_u32_e32 v83, -16, v82
	v_cvt_f32_i32_e32 v83, v83
	v_add_u32_e32 v86, -11, v82
	v_cvt_f32_i32_e32 v86, v86
	v_and_b32_e32 v84, 0x7fffffff, v84
	v_pk_fma_f32 v[214:215], v[162:163], v[84:85], v[146:147] op_sel_hi:[1,1,0]
	v_and_b32_e32 v85, 0x7fffffff, v83
	v_subrev_u32_e32 v83, 18, v82
	v_cvt_f32_i32_e32 v83, v83
	v_and_b32_e32 v84, 0x7fffffff, v86
	v_pk_fma_f32 v[216:217], v[162:163], v[84:85], v[146:147] op_sel_hi:[1,1,0]
	v_subrev_u32_e32 v84, 17, v82
	v_cvt_f32_i32_e32 v84, v84
	v_and_b32_e32 v85, 0x7fffffff, v83
	v_subrev_u32_e32 v83, 24, v82
	v_subrev_u32_e32 v86, 19, v82
	v_cvt_f32_i32_e32 v83, v83
	v_cvt_f32_i32_e32 v86, v86
	v_and_b32_e32 v84, 0x7fffffff, v84
	v_pk_fma_f32 v[218:219], v[162:163], v[84:85], v[146:147] op_sel_hi:[1,1,0]
	v_and_b32_e32 v85, 0x7fffffff, v83
	v_and_b32_e32 v84, 0x7fffffff, v86
	v_pk_fma_f32 v[220:221], v[162:163], v[84:85], v[146:147] op_sel_hi:[1,1,0]
	v_subrev_u32_e32 v83, 26, v82
	v_subrev_u32_e32 v84, 25, v82
	v_cvt_f32_i32_e32 v83, v83
	v_cvt_f32_i32_e32 v84, v84
	v_subrev_u32_e32 v82, 27, v82
	v_cvt_f32_i32_e32 v85, v82
	v_and_b32_e32 v83, 0x7fffffff, v83
	v_and_b32_e32 v82, 0x7fffffff, v84
	v_mov_b32_e32 v97, v210
	v_pk_fma_f32 v[222:223], v[162:163], v[82:83], v[146:147] op_sel_hi:[1,1,0]
	v_fma_f32 v224, -v158, |v85|, v146
	v_mov_b64_e32 v[82:83], v[96:97]
	v_mov_b64_e32 v[84:85], v[98:99]
	v_mov_b64_e32 v[86:87], v[100:101]
	v_mov_b64_e32 v[88:89], v[102:103]
	v_mov_b64_e32 v[90:91], v[104:105]
	v_mov_b64_e32 v[92:93], v[106:107]
	v_mov_b64_e32 v[94:95], v[108:109]
	v_mov_b64_e32 v[96:97], v[110:111]
	v_mov_b32_e32 v84, v211
	v_mov_b32_e32 v85, v212
	v_mov_b32_e32 v86, v213
	v_mov_b32_e32 v87, v214
	v_mov_b32_e32 v88, v215
	v_mov_b32_e32 v89, v216
	v_mov_b32_e32 v90, v217
	v_mov_b32_e32 v91, v218
	v_mov_b32_e32 v92, v219
	v_mov_b32_e32 v93, v220
	v_mov_b32_e32 v94, v221
	v_mov_b32_e32 v95, v222
	v_mov_b32_e32 v96, v223
	v_mov_b32_e32 v97, v224
	s_mov_b64 s[48:49], -1
	s_and_b64 vcc, exec, s[44:45]
	s_cbranch_vccnz .LBB0_226
	s_branch .LBB0_227
.LBB0_225:
	v_cndmask_b32_e64 v244, -v158, v158, s[48:49]
	v_fma_f32 v82, 0, v244, v96
	v_add_f32_e32 v83, v244, v96
	v_pk_fma_f32 v[84:85], v[244:245], s[26:27], v[96:97] op_sel_hi:[0,1,0]
	v_pk_fma_f32 v[86:87], v[244:245], s[28:29], v[96:97] op_sel_hi:[0,1,0]
	v_pk_fma_f32 v[88:89], v[244:245], s[30:31], v[96:97] op_sel_hi:[0,1,0]
	v_pk_fma_f32 v[90:91], v[244:245], s[34:35], v[96:97] op_sel_hi:[0,1,0]
	v_pk_fma_f32 v[92:93], v[244:245], s[36:37], v[96:97] op_sel_hi:[0,1,0]
	v_pk_fma_f32 v[94:95], v[244:245], s[14:15], v[96:97] op_sel_hi:[0,1,0]
	v_pk_fma_f32 v[96:97], v[244:245], s[10:11], v[96:97] op_sel_hi:[0,1,0]
	s_mov_b64 s[48:49], -1
	s_and_b64 vcc, exec, s[44:45]
	s_cbranch_vccz .LBB0_227

.LBB0_229:
	s_barrier
	s_and_b32 s0, s97, 0xf80
	s_mul_i32 s18, s0, 0x1200
	v_lshl_add_u64 v[248:249], v[160:161], 0, s[18:19]
	v_lshl_add_u64 v[250:251], v[248:249], 0, s[22:23]
	s_mov_b32 m0, s93
	s_nop 0
	global_load_lds_dwordx4 v[250:251], off

.LBB0_234:
	v_mfma_f32_32x32x16_bf16 v[50:65], v[130:133], v[66:69], v[50:65]
	ds_read_b128 v[182:185], v169
	ds_read_b128 v[198:201], v170
	ds_read_b128 v[202:205], v171
	v_exp_f32_e32 v149, v82
	v_exp_f32_e32 v150, v83
	s_add_i32 s0, s97, 0xffffff80
	s_and_b32 s0, s0, 0xf80
	s_cmp_lt_u32 s0, s84
	s_cselect_b64 s[44:45], -1, 0
	s_cmp_lg_u32 s0, s84
	v_mfma_f32_32x32x16_bf16 v[34:49], v[126:129], v[66:69], v[34:49]
	ds_read_b128 v[206:209], v172
	ds_read_b64_tr_b16 v[130:131], v173 offset:57344
	ds_read_b64_tr_b16 v[132:133], v174 offset:57344
	v_exp_f32_e32 v151, v84
	v_exp_f32_e32 v152, v85
	v_mfma_f32_32x32x16_bf16 v[18:33], v[122:125], v[66:69], v[18:33]
	ds_read_b64_tr_b16 v[126:127], v175 offset:57344
	ds_read_b64_tr_b16 v[128:129], v176 offset:57344
	ds_read_b64_tr_b16 v[122:123], v177 offset:57344
	v_exp_f32_e32 v153, v86
	v_exp_f32_e32 v164, v87
	v_mfma_f32_32x32x16_bf16 v[2:17], v[118:121], v[66:69], v[2:17]
	ds_read_b64_tr_b16 v[124:125], v178 offset:57344
	ds_read_b64_tr_b16 v[118:119], v179 offset:57344
	ds_read_b64_tr_b16 v[120:121], v180 offset:57344
	v_exp_f32_e32 v181, v88
	v_exp_f32_e32 v225, v89
	v_lshl_add_u64 v[250:251], v[248:249], 0, s[56:57]
	s_mov_b32 m0, s95
	s_nop 0
	global_load_lds_dwordx4 v[250:251], off
	v_or_b32_e32 v66, s0, v166
	v_sub_u32_e32 v66, v167, v66
	v_cvt_f32_i32_e32 v67, v66
	v_fma_f32 v80, -v158, |v67|, v146
	v_mfma_f32_32x32x16_bf16 v[50:65], v[114:117], v[70:73], v[50:65]
	ds_read_b64_tr_b16 v[114:115], v173 offset:61440
	ds_read_b64_tr_b16 v[116:117], v174 offset:61440
	v_exp_f32_e32 v226, v90
	v_exp_f32_e32 v227, v91
	v_mfma_f32_32x32x16_bf16 v[34:49], v[134:137], v[70:73], v[34:49]
	ds_read_b64_tr_b16 v[134:135], v175 offset:61440
	ds_read_b64_tr_b16 v[136:137], v176 offset:61440
	v_exp_f32_e32 v239, v92
	v_exp_f32_e32 v240, v93
	v_mfma_f32_32x32x16_bf16 v[18:33], v[138:141], v[70:73], v[18:33]
	ds_read_b64_tr_b16 v[138:139], v177 offset:61440
	ds_read_b64_tr_b16 v[140:141], v178 offset:61440
	v_exp_f32_e32 v241, v94
	v_exp_f32_e32 v242, v95
	v_mfma_f32_32x32x16_bf16 v[2:17], v[142:145], v[70:73], v[2:17]
	ds_read_b64_tr_b16 v[142:143], v179 offset:61440
	ds_read_b64_tr_b16 v[144:145], v180 offset:61440
	v_exp_f32_e32 v243, v96
	v_exp_f32_e32 v246, v97
	s_cbranch_scc1 .LBB0_236
	v_add_u32_e32 v67, -2, v66
	v_cvt_f32_i32_e32 v67, v67
	v_add_u32_e32 v68, -1, v66
	v_cvt_f32_i32_e32 v68, v68
	v_add_u32_e32 v70, -8, v66
	v_and_b32_e32 v69, 0x7fffffff, v67
	v_add_u32_e32 v67, -3, v66
	v_cvt_f32_i32_e32 v67, v67
	v_cvt_f32_i32_e32 v70, v70
	v_and_b32_e32 v68, 0x7fffffff, v68
	v_pk_fma_f32 v[210:211], v[162:163], v[68:69], v[146:147] op_sel_hi:[1,1,0]
	v_and_b32_e32 v68, 0x7fffffff, v67
	v_add_u32_e32 v67, -10, v66
	v_cvt_f32_i32_e32 v67, v67
	v_and_b32_e32 v69, 0x7fffffff, v70
	v_pk_fma_f32 v[212:213], v[162:163], v[68:69], v[146:147] op_sel_hi:[1,1,0]
	v_add_u32_e32 v68, -9, v66
	v_cvt_f32_i32_e32 v68, v68
	v_and_b32_e32 v69, 0x7fffffff, v67
	v_add_u32_e32 v67, -16, v66
	v_cvt_f32_i32_e32 v67, v67
	v_add_u32_e32 v70, -11, v66
	v_cvt_f32_i32_e32 v70, v70
	v_and_b32_e32 v68, 0x7fffffff, v68
	v_pk_fma_f32 v[214:215], v[162:163], v[68:69], v[146:147] op_sel_hi:[1,1,0]
	v_and_b32_e32 v69, 0x7fffffff, v67
	v_subrev_u32_e32 v67, 18, v66
	v_cvt_f32_i32_e32 v67, v67
	v_and_b32_e32 v68, 0x7fffffff, v70
	v_pk_fma_f32 v[216:217], v[162:163], v[68:69], v[146:147] op_sel_hi:[1,1,0]
	v_subrev_u32_e32 v68, 17, v66
	v_cvt_f32_i32_e32 v68, v68
	v_and_b32_e32 v69, 0x7fffffff, v67
	v_subrev_u32_e32 v67, 24, v66
	v_subrev_u32_e32 v70, 19, v66
	v_cvt_f32_i32_e32 v67, v67
	v_cvt_f32_i32_e32 v70, v70
	v_and_b32_e32 v68, 0x7fffffff, v68
	v_pk_fma_f32 v[218:219], v[162:163], v[68:69], v[146:147] op_sel_hi:[1,1,0]
	v_and_b32_e32 v69, 0x7fffffff, v67
	v_and_b32_e32 v68, 0x7fffffff, v70
	v_pk_fma_f32 v[220:221], v[162:163], v[68:69], v[146:147] op_sel_hi:[1,1,0]
	v_subrev_u32_e32 v67, 26, v66
	v_subrev_u32_e32 v68, 25, v66
	v_cvt_f32_i32_e32 v67, v67
	v_cvt_f32_i32_e32 v68, v68
	v_subrev_u32_e32 v66, 27, v66
	v_cvt_f32_i32_e32 v69, v66
	v_and_b32_e32 v67, 0x7fffffff, v67
	v_and_b32_e32 v66, 0x7fffffff, v68
	v_mov_b32_e32 v81, v210
	v_pk_fma_f32 v[222:223], v[162:163], v[66:67], v[146:147] op_sel_hi:[1,1,0]
	v_fma_f32 v224, -v158, |v69|, v146
	v_mov_b64_e32 v[66:67], v[80:81]
	v_mov_b64_e32 v[68:69], v[82:83]
	v_mov_b64_e32 v[70:71], v[84:85]
	v_mov_b64_e32 v[72:73], v[86:87]
	v_mov_b64_e32 v[74:75], v[88:89]
	v_mov_b64_e32 v[76:77], v[90:91]
	v_mov_b64_e32 v[78:79], v[92:93]
	v_mov_b64_e32 v[80:81], v[94:95]
	v_mov_b32_e32 v68, v211
	v_mov_b32_e32 v69, v212
	v_mov_b32_e32 v70, v213
	v_mov_b32_e32 v71, v214
	v_mov_b32_e32 v72, v215
	v_mov_b32_e32 v73, v216
	v_mov_b32_e32 v74, v217
	v_mov_b32_e32 v75, v218
	v_mov_b32_e32 v76, v219
	v_mov_b32_e32 v77, v220
	v_mov_b32_e32 v78, v221
	v_mov_b32_e32 v79, v222
	v_mov_b32_e32 v80, v223
	v_mov_b32_e32 v81, v224
	s_branch .LBB0_237

.LBB0_237:
	v_lshl_add_u64 v[250:251], v[248:249], 0, s[68:69]
	s_mov_b32 m0, s94
	s_nop 0
	global_load_lds_dwordx4 v[250:251], off
	v_add_f32_e32 v147, v148, v147
	s_waitcnt lgkmcnt(0)
	v_mfma_f32_32x32x16_bf16 v[66:81], v[182:185], v[98:101], v[66:81]
	v_add_f32_e32 v148, 0, v149
	v_add_f32_e32 v148, v150, v148
	v_mfma_f32_32x32x16_bf16 v[66:81], v[198:201], v[102:105], v[66:81]
	v_add_f32_e32 v148, v151, v148
	v_add_f32_e32 v148, v152, v148
	v_add_f32_e32 v148, v153, v148
	v_mfma_f32_32x32x16_bf16 v[66:81], v[202:205], v[106:109], v[66:81]
	v_add_f32_e32 v148, v164, v148
	v_add_f32_e32 v148, v181, v148
	v_add_f32_e32 v148, v225, v148
	v_add_f32_e32 v148, v226, v148
	v_add_f32_e32 v148, v227, v148
	v_mfma_f32_32x32x16_bf16 v[66:81], v[206:209], v[110:113], v[66:81]
	v_add_f32_e32 v148, v239, v148
	v_add_f32_e32 v148, v240, v148
	v_add_f32_e32 v148, v241, v148
	v_add_f32_e32 v148, v242, v148
	v_add_f32_e32 v148, v243, v148
	v_add_f32_e32 v148, v246, v148
	v_cmp_nge_f32_e32 vcc, s12, v148
	s_cbranch_vccz .LBB0_239
	v_max_f32_e32 v146, v83, v83
	v_max_f32_e32 v148, v82, v82
	v_max_f32_e32 v146, v148, v146
	v_max3_f32 v146, v146, v84, v85
	v_max3_f32 v146, v146, v86, v87
	v_max3_f32 v146, v146, v88, v89
	v_max3_f32 v146, v146, v90, v91
	v_max3_f32 v146, v146, v92, v93
	v_max3_f32 v146, v146, v94, v95
	v_max3_f32 v146, v146, v96, v97
	ds_bpermute_b32 v148, v159, v146
	s_waitcnt lgkmcnt(0)
	v_max3_f32 v148, v146, v148, 0
	v_sub_f32_e32 v82, v82, v148
	v_exp_f32_e32 v82, v82
	v_sub_f32_e32 v83, v83, v148
	v_exp_f32_e32 v83, v83
	v_sub_f32_e32 v84, v84, v148
	v_exp_f32_e32 v84, v84
	v_sub_f32_e32 v85, v85, v148
	v_exp_f32_e32 v85, v85
	v_sub_f32_e32 v86, v86, v148
	v_sub_f32_e32 v87, v87, v148
	v_add_f32_e32 v149, 0, v82
	v_exp_f32_e32 v86, v86
	v_exp_f32_e32 v87, v87
	v_add_f32_e32 v149, v83, v149
	v_sub_f32_e32 v88, v88, v148
	v_sub_f32_e32 v89, v89, v148
	v_add_f32_e32 v149, v84, v149
	v_exp_f32_e32 v88, v88
	v_exp_f32_e32 v89, v89
	v_add_f32_e32 v149, v85, v149
	v_add_f32_e32 v149, v86, v149
	v_cvt_pk_bf16_f32 v82, v82, v83
	v_cvt_pk_bf16_f32 v83, v84, v85
	v_cvt_pk_bf16_f32 v84, v86, v87
	v_sub_f32_e32 v86, v90, v148
	v_add_f32_e32 v149, v87, v149
	v_exp_f32_e32 v86, v86
	v_sub_f32_e32 v87, v91, v148
	v_add_f32_e32 v149, v88, v149
	v_cvt_pk_bf16_f32 v85, v88, v89
	v_exp_f32_e32 v87, v87
	v_sub_f32_e32 v88, v92, v148
	v_add_f32_e32 v149, v89, v149
	v_exp_f32_e32 v88, v88
	v_sub_f32_e32 v89, v93, v148
	v_exp_f32_e32 v89, v89
	v_sub_f32_e32 v91, v94, v148
	v_add_f32_e32 v90, v86, v149
	v_exp_f32_e32 v91, v91
	v_sub_f32_e32 v92, v95, v148
	v_add_f32_e32 v90, v87, v90
	v_exp_f32_e32 v92, v92
	v_sub_f32_e32 v93, v96, v148
	v_add_f32_e32 v90, v88, v90
	v_exp_f32_e32 v93, v93
	v_sub_f32_e32 v94, v97, v148
	v_exp_f32_e64 v146, -v148
	v_add_f32_e32 v90, v89, v90
	v_exp_f32_e32 v94, v94
	v_add_f32_e32 v90, v91, v90
	v_add_f32_e32 v90, v92, v90
	v_add_f32_e32 v0, v0, v148
	v_add_f32_e32 v90, v93, v90
	v_pk_mul_f32 v[64:65], v[64:65], v[146:147] op_sel_hi:[1,0]
	v_pk_mul_f32 v[62:63], v[62:63], v[146:147] op_sel_hi:[1,0]
	v_pk_mul_f32 v[60:61], v[60:61], v[146:147] op_sel_hi:[1,0]
	v_pk_mul_f32 v[58:59], v[58:59], v[146:147] op_sel_hi:[1,0]
	v_pk_mul_f32 v[56:57], v[56:57], v[146:147] op_sel_hi:[1,0]
	v_pk_mul_f32 v[54:55], v[54:55], v[146:147] op_sel_hi:[1,0]
	v_pk_mul_f32 v[52:53], v[52:53], v[146:147] op_sel_hi:[1,0]
	v_pk_mul_f32 v[50:51], v[50:51], v[146:147] op_sel_hi:[1,0]
	v_pk_mul_f32 v[48:49], v[48:49], v[146:147] op_sel_hi:[1,0]
	v_pk_mul_f32 v[46:47], v[46:47], v[146:147] op_sel_hi:[1,0]
	v_pk_mul_f32 v[44:45], v[44:45], v[146:147] op_sel_hi:[1,0]
	v_pk_mul_f32 v[42:43], v[42:43], v[146:147] op_sel_hi:[1,0]
	v_pk_mul_f32 v[40:41], v[40:41], v[146:147] op_sel_hi:[1,0]
	v_pk_mul_f32 v[38:39], v[38:39], v[146:147] op_sel_hi:[1,0]
	v_pk_mul_f32 v[36:37], v[36:37], v[146:147] op_sel_hi:[1,0]
	v_pk_mul_f32 v[34:35], v[34:35], v[146:147] op_sel_hi:[1,0]
	v_pk_mul_f32 v[32:33], v[32:33], v[146:147] op_sel_hi:[1,0]
	v_pk_mul_f32 v[30:31], v[30:31], v[146:147] op_sel_hi:[1,0]
	v_pk_mul_f32 v[28:29], v[28:29], v[146:147] op_sel_hi:[1,0]
	v_pk_mul_f32 v[26:27], v[26:27], v[146:147] op_sel_hi:[1,0]
	v_pk_mul_f32 v[24:25], v[24:25], v[146:147] op_sel_hi:[1,0]
	v_pk_mul_f32 v[22:23], v[22:23], v[146:147] op_sel_hi:[1,0]
	v_pk_mul_f32 v[20:21], v[20:21], v[146:147] op_sel_hi:[1,0]
	v_pk_mul_f32 v[18:19], v[18:19], v[146:147] op_sel_hi:[1,0]
	v_pk_mul_f32 v[16:17], v[16:17], v[146:147] op_sel_hi:[1,0]
	v_pk_mul_f32 v[14:15], v[14:15], v[146:147] op_sel_hi:[1,0]
	v_pk_mul_f32 v[12:13], v[12:13], v[146:147] op_sel_hi:[1,0]
	v_pk_mul_f32 v[10:11], v[10:11], v[146:147] op_sel_hi:[1,0]
	v_pk_mul_f32 v[8:9], v[8:9], v[146:147] op_sel_hi:[1,0]
	v_pk_mul_f32 v[6:7], v[6:7], v[146:147] op_sel_hi:[1,0]
	v_pk_mul_f32 v[4:5], v[4:5], v[146:147] op_sel_hi:[1,0]
	v_pk_mul_f32 v[2:3], v[2:3], v[146:147] op_sel_hi:[1,0]
	v_sub_f32_e32 v81, v81, v148
	v_sub_f32_e32 v80, v80, v148
	v_sub_f32_e32 v79, v79, v148
	v_sub_f32_e32 v78, v78, v148
	v_sub_f32_e32 v77, v77, v148
	v_sub_f32_e32 v76, v76, v148
	v_sub_f32_e32 v75, v75, v148
	v_sub_f32_e32 v74, v74, v148
	v_sub_f32_e32 v73, v73, v148
	v_sub_f32_e32 v72, v72, v148
	v_sub_f32_e32 v71, v71, v148
	v_sub_f32_e32 v70, v70, v148
	v_sub_f32_e32 v69, v69, v148
	v_sub_f32_e32 v68, v68, v148
	v_sub_f32_e32 v67, v67, v148
	v_sub_f32_e32 v66, v66, v148
	v_add_f32_e32 v148, v94, v90
	v_cvt_pk_bf16_f32 v86, v86, v87
	v_cvt_pk_bf16_f32 v87, v88, v89
	v_cvt_pk_bf16_f32 v88, v91, v92
	v_cvt_pk_bf16_f32 v89, v93, v94
	v_mul_f32_e32 v147, v147, v146
	v_xor_b32_e32 v146, 0x80000000, v0
	s_branch .LBB0_240

.LBB0_240:
	v_mfma_f32_32x32x16_bf16 v[50:65], v[130:133], v[82:85], v[50:65]
	s_or_b32 s0, s0, 32
	s_cmp_lt_u32 s0, s84
	s_cselect_b64 s[44:45], -1, 0
	s_cmp_lg_u32 s0, s84
	v_mfma_f32_32x32x16_bf16 v[34:49], v[126:129], v[82:85], v[34:49]
	v_mfma_f32_32x32x16_bf16 v[18:33], v[122:125], v[82:85], v[18:33]
	v_mfma_f32_32x32x16_bf16 v[2:17], v[118:121], v[82:85], v[2:17]
	v_lshl_add_u64 v[250:251], v[248:249], 0, s[46:47]
	s_mov_b32 m0, s96
	s_nop 0
	global_load_lds_dwordx4 v[250:251], off
	v_or_b32_e32 v82, s0, v166
	v_sub_u32_e32 v83, v167, v82
	v_cvt_f32_i32_e32 v82, v83
	v_fma_f32 v82, -v158, |v82|, v146
	v_mfma_f32_32x32x16_bf16 v[50:65], v[114:117], v[86:89], v[50:65]
	v_mfma_f32_32x32x16_bf16 v[34:49], v[134:137], v[86:89], v[34:49]
	v_mfma_f32_32x32x16_bf16 v[18:33], v[138:141], v[86:89], v[18:33]
	v_mfma_f32_32x32x16_bf16 v[2:17], v[142:145], v[86:89], v[2:17]
	s_cbranch_scc0 .LBB0_180
	v_cndmask_b32_e64 v96, -v158, v158, s[44:45]
	v_fma_f32 v114, 0, v96, v82
	v_add_f32_e32 v83, v96, v82
	v_pk_fma_f32 v[84:85], v[96:97], s[26:27], v[82:83] op_sel_hi:[0,1,0]
	v_pk_fma_f32 v[86:87], v[96:97], s[28:29], v[82:83] op_sel_hi:[0,1,0]
	v_pk_fma_f32 v[88:89], v[96:97], s[30:31], v[82:83] op_sel_hi:[0,1,0]
	v_pk_fma_f32 v[90:91], v[96:97], s[34:35], v[82:83] op_sel_hi:[0,1,0]
	v_pk_fma_f32 v[92:93], v[96:97], s[36:37], v[82:83] op_sel_hi:[0,1,0]
	v_pk_fma_f32 v[94:95], v[96:97], s[14:15], v[82:83] op_sel_hi:[0,1,0]
	v_pk_fma_f32 v[96:97], v[96:97], s[10:11], v[82:83] op_sel_hi:[0,1,0]
	v_mov_b32_e32 v82, v114
	s_branch .LBB0_181

; __global__ void __launch_bounds__(512, 2) fwd_kernel(Args a0) {
	.amdhsa_kernel _Z10fwd_kernel4Args
		.amdhsa_group_segment_fixed_size 0
		.amdhsa_private_segment_fixed_size 0
		.amdhsa_kernarg_size 432
		.amdhsa_user_sgpr_count 2
		.amdhsa_user_sgpr_dispatch_ptr 0
		.amdhsa_user_sgpr_queue_ptr 0
		.amdhsa_user_sgpr_kernarg_segment_ptr 1
		.amdhsa_user_sgpr_dispatch_id 0
		.amdhsa_user_sgpr_kernarg_preload_length 0
		.amdhsa_user_sgpr_kernarg_preload_offset 0
		.amdhsa_user_sgpr_private_segment_size 0
		.amdhsa_uses_dynamic_stack 0
		.amdhsa_enable_private_segment 0
		.amdhsa_system_sgpr_workgroup_id_x 1
		.amdhsa_system_sgpr_workgroup_id_y 0
		.amdhsa_system_sgpr_workgroup_id_z 0
		.amdhsa_system_sgpr_workgroup_info 0
		.amdhsa_system_vgpr_workitem_id 2
		.amdhsa_next_free_vgpr 255
		.amdhsa_next_free_sgpr 102
		.amdhsa_accum_offset 256
		.amdhsa_reserve_vcc 1
		.amdhsa_float_round_mode_32 0
		.amdhsa_float_round_mode_16_64 0
		.amdhsa_float_denorm_mode_32 3
		.amdhsa_float_denorm_mode_16_64 3
		.amdhsa_dx10_clamp 1
		.amdhsa_ieee_mode 1
		.amdhsa_fp16_overflow 0
		.amdhsa_tg_split 0
		.amdhsa_exception_fp_ieee_invalid_op 0
		.amdhsa_exception_fp_denorm_src 0
		.amdhsa_exception_fp_ieee_div_zero 0
		.amdhsa_exception_fp_ieee_overflow 0
		.amdhsa_exception_fp_ieee_underflow 0
		.amdhsa_exception_fp_ieee_inexact 0
		.amdhsa_exception_int_div_zero 0
	.end_amdhsa_kernel

; __global__ void __launch_bounds__(512, 2) fwd_kernel(Args a0) {
amdhsa.kernels:
  - .agpr_count:     0
    .args:
      - .offset:         0
        .size:           176
        .value_kind:     by_value
      - .offset:         176
        .size:           4
        .value_kind:     hidden_block_count_x
      - .offset:         180
        .size:           4
        .value_kind:     hidden_block_count_y
      - .offset:         184
        .size:           4
        .value_kind:     hidden_block_count_z
      - .offset:         188
        .size:           2
        .value_kind:     hidden_group_size_x
      - .offset:         190
        .size:           2
        .value_kind:     hidden_group_size_y
      - .offset:         192
        .size:           2
        .value_kind:     hidden_group_size_z
      - .offset:         194
        .size:           2
        .value_kind:     hidden_remainder_x
      - .offset:         196
        .size:           2
        .value_kind:     hidden_remainder_y
      - .offset:         198
        .size:           2
        .value_kind:     hidden_remainder_z
      - .offset:         216
        .size:           8
        .value_kind:     hidden_global_offset_x
      - .offset:         224
        .size:           8
        .value_kind:     hidden_global_offset_y
      - .offset:         232
        .size:           8
        .value_kind:     hidden_global_offset_z
      - .offset:         240
        .size:           2
        .value_kind:     hidden_grid_dims
      - .offset:         264
        .size:           8
        .value_kind:     hidden_multigrid_sync_arg
      - .offset:         296
        .size:           4
        .value_kind:     hidden_dynamic_lds_size
    .group_segment_fixed_size: 0
    .kernarg_segment_align: 8
    .kernarg_segment_size: 432
    .language:       OpenCL C
    .language_version:
      - 2
      - 0
    .max_flat_workgroup_size: 512
    .name:           _Z10fwd_kernel4Args
    .private_segment_fixed_size: 0
    .sgpr_count:     108
    .sgpr_spill_count: 151
    .symbol:         _Z10fwd_kernel4Args.kd
    .uniform_work_group_size: 1
    .uses_dynamic_stack: false
    .vgpr_count:     255
    .vgpr_spill_count: 0
    .wavefront_size: 64
